# MT=8 loop: barrier 2 right after B-fragment reads so B and A DMAs issue early
# baseline (speedup 1.0000x reference)
.Lg8p2_loop:
	s_waitcnt vmcnt(0) lgkmcnt(0)
	s_barrier
	ds_read_b128 v[128:131], v241 offset:0
	ds_read_b128 v[136:139], v241 offset:2048
	ds_read_b128 v[144:147], v241 offset:4096
	ds_read_b128 v[152:155], v241 offset:6144
	ds_read_b128 v[132:135], v242 offset:0
	ds_read_b128 v[140:143], v242 offset:2048
	ds_read_b128 v[148:151], v242 offset:4096
	ds_read_b128 v[156:159], v242 offset:6144
	s_waitcnt lgkmcnt(0)
	s_barrier
	s_add_u32 m0, s4, 65536
	ds_read_b128 v[160:163], v243 offset:0
	global_load_lds_dwordx4 v226, s[100:101]
	s_add_u32 m0, s4, 69632
	ds_read_b128 v[164:167], v243 offset:2048
	global_load_lds_dwordx4 v227, s[100:101]
	s_add_u32 m0, s4, 73728
	ds_read_b128 v[168:171], v243 offset:4096
	global_load_lds_dwordx4 v248, s[100:101]
	s_add_u32 m0, s4, 77824
	ds_read_b128 v[172:175], v243 offset:6144
	global_load_lds_dwordx4 v249, s[100:101]
	s_add_u32 m0, s4, 32768
	s_nop 0
	global_load_lds_dwordx4 v226, s[98:99]
	s_add_u32 m0, s4, 36864
	s_nop 0
	global_load_lds_dwordx4 v227, s[98:99]
	s_add_u32 m0, s4, 40960
	s_nop 0
	global_load_lds_dwordx4 v248, s[98:99]
	s_add_u32 m0, s4, 45056
	s_nop 0
	global_load_lds_dwordx4 v249, s[98:99]
	s_add_u32 m0, s4, 49152
	s_nop 0
	global_load_lds_dwordx4 v247, s[98:99]
	s_add_u32 m0, s4, 53248
	s_nop 0
	global_load_lds_dwordx4 v244, s[98:99]
	s_add_u32 m0, s4, 57344
	s_nop 0
	global_load_lds_dwordx4 v245, s[98:99]
	s_add_u32 m0, s4, 61440
	s_nop 0
	global_load_lds_dwordx4 v246, s[98:99]
	s_add_u32 s98, s98, 0x80
	s_addc_u32 s99, s99, 0
	s_add_u32 s100, s100, 0x80
	s_addc_u32 s101, s101, 0
	s_waitcnt lgkmcnt(3)
	v_mfma_f32_16x16x32_bf16 v[124:127], v[128:131], v[160:163], v[124:127]
	ds_read_b128 v[176:179], v243 offset:8192
	v_mfma_f32_16x16x32_bf16 v[120:123], v[136:139], v[160:163], v[120:123]
	v_mfma_f32_16x16x32_bf16 v[116:119], v[144:147], v[160:163], v[116:119]
	v_mfma_f32_16x16x32_bf16 v[112:115], v[152:155], v[160:163], v[112:115]
	s_waitcnt lgkmcnt(3)
	v_mfma_f32_16x16x32_bf16 v[108:111], v[128:131], v[164:167], v[108:111]
	ds_read_b128 v[180:183], v243 offset:10240
	v_mfma_f32_16x16x32_bf16 v[104:107], v[136:139], v[164:167], v[104:107]
	v_mfma_f32_16x16x32_bf16 v[100:103], v[144:147], v[164:167], v[100:103]
	v_mfma_f32_16x16x32_bf16 v[96:99], v[152:155], v[164:167], v[96:99]
	s_waitcnt lgkmcnt(3)
	v_mfma_f32_16x16x32_bf16 v[92:95], v[128:131], v[168:171], v[92:95]
	ds_read_b128 v[160:163], v243 offset:12288
	v_mfma_f32_16x16x32_bf16 v[88:91], v[136:139], v[168:171], v[88:91]
	v_mfma_f32_16x16x32_bf16 v[84:87], v[144:147], v[168:171], v[84:87]
	v_mfma_f32_16x16x32_bf16 v[80:83], v[152:155], v[168:171], v[80:83]
	s_waitcnt lgkmcnt(3)
	v_mfma_f32_16x16x32_bf16 v[76:79], v[128:131], v[172:175], v[76:79]
	ds_read_b128 v[164:167], v243 offset:14336
	v_mfma_f32_16x16x32_bf16 v[64:67], v[136:139], v[172:175], v[64:67]
	v_mfma_f32_16x16x32_bf16 v[72:75], v[144:147], v[172:175], v[72:75]
	v_mfma_f32_16x16x32_bf16 v[68:71], v[152:155], v[172:175], v[68:71]
	s_waitcnt lgkmcnt(3)
	v_mfma_f32_16x16x32_bf16 v[48:51], v[128:131], v[176:179], v[48:51]
	ds_read_b128 v[168:171], v240 offset:0
	v_mfma_f32_16x16x32_bf16 v[52:55], v[136:139], v[176:179], v[52:55]
	v_mfma_f32_16x16x32_bf16 v[56:59], v[144:147], v[176:179], v[56:59]
	v_mfma_f32_16x16x32_bf16 v[36:39], v[152:155], v[176:179], v[36:39]
	s_waitcnt lgkmcnt(3)
	v_mfma_f32_16x16x32_bf16 v[8:11], v[128:131], v[180:183], v[8:11]
	ds_read_b128 v[172:175], v240 offset:2048
	v_mfma_f32_16x16x32_bf16 v[12:15], v[136:139], v[180:183], v[12:15]
	v_mfma_f32_16x16x32_bf16 v[24:27], v[144:147], v[180:183], v[24:27]
	v_mfma_f32_16x16x32_bf16 v[32:35], v[152:155], v[180:183], v[32:35]
	s_waitcnt lgkmcnt(3)
	v_mfma_f32_16x16x32_bf16 v[0:3], v[128:131], v[160:163], v[0:3]
	ds_read_b128 v[176:179], v240 offset:4096
	v_mfma_f32_16x16x32_bf16 v[4:7], v[136:139], v[160:163], v[4:7]
	v_mfma_f32_16x16x32_bf16 v[44:47], v[144:147], v[160:163], v[44:47]
	v_mfma_f32_16x16x32_bf16 v[40:43], v[152:155], v[160:163], v[40:43]
	s_waitcnt lgkmcnt(3)
	v_mfma_f32_16x16x32_bf16 v[28:31], v[128:131], v[164:167], v[28:31]
	ds_read_b128 v[180:183], v240 offset:6144
	v_mfma_f32_16x16x32_bf16 v[20:23], v[136:139], v[164:167], v[20:23]
	v_mfma_f32_16x16x32_bf16 v[16:19], v[144:147], v[164:167], v[16:19]
	v_mfma_f32_16x16x32_bf16 v[60:63], v[152:155], v[164:167], v[60:63]
	s_waitcnt lgkmcnt(3)
	v_mfma_f32_16x16x32_bf16 v[124:127], v[132:135], v[168:171], v[124:127]
	ds_read_b128 v[160:163], v240 offset:8192
	v_mfma_f32_16x16x32_bf16 v[120:123], v[140:143], v[168:171], v[120:123]
	v_mfma_f32_16x16x32_bf16 v[116:119], v[148:151], v[168:171], v[116:119]
	v_mfma_f32_16x16x32_bf16 v[112:115], v[156:159], v[168:171], v[112:115]
	s_waitcnt lgkmcnt(3)
	v_mfma_f32_16x16x32_bf16 v[108:111], v[132:135], v[172:175], v[108:111]
	ds_read_b128 v[164:167], v240 offset:10240
	v_mfma_f32_16x16x32_bf16 v[104:107], v[140:143], v[172:175], v[104:107]
	v_mfma_f32_16x16x32_bf16 v[100:103], v[148:151], v[172:175], v[100:103]
	v_mfma_f32_16x16x32_bf16 v[96:99], v[156:159], v[172:175], v[96:99]
	s_waitcnt lgkmcnt(3)
	v_mfma_f32_16x16x32_bf16 v[92:95], v[132:135], v[176:179], v[92:95]
	ds_read_b128 v[168:171], v240 offset:12288
	v_mfma_f32_16x16x32_bf16 v[88:91], v[140:143], v[176:179], v[88:91]
	v_mfma_f32_16x16x32_bf16 v[84:87], v[148:151], v[176:179], v[84:87]
	v_mfma_f32_16x16x32_bf16 v[80:83], v[156:159], v[176:179], v[80:83]
	s_waitcnt lgkmcnt(3)
	v_mfma_f32_16x16x32_bf16 v[76:79], v[132:135], v[180:183], v[76:79]
	ds_read_b128 v[172:175], v240 offset:14336
	v_mfma_f32_16x16x32_bf16 v[64:67], v[140:143], v[180:183], v[64:67]
	v_mfma_f32_16x16x32_bf16 v[72:75], v[148:151], v[180:183], v[72:75]
	v_mfma_f32_16x16x32_bf16 v[68:71], v[156:159], v[180:183], v[68:71]
	s_waitcnt lgkmcnt(3)
	v_mfma_f32_16x16x32_bf16 v[48:51], v[132:135], v[160:163], v[48:51]
	v_mfma_f32_16x16x32_bf16 v[52:55], v[140:143], v[160:163], v[52:55]
	v_mfma_f32_16x16x32_bf16 v[56:59], v[148:151], v[160:163], v[56:59]
	v_mfma_f32_16x16x32_bf16 v[36:39], v[156:159], v[160:163], v[36:39]
	s_waitcnt lgkmcnt(2)
	v_mfma_f32_16x16x32_bf16 v[8:11], v[132:135], v[164:167], v[8:11]
	v_mfma_f32_16x16x32_bf16 v[12:15], v[140:143], v[164:167], v[12:15]
	v_mfma_f32_16x16x32_bf16 v[24:27], v[148:151], v[164:167], v[24:27]
	v_mfma_f32_16x16x32_bf16 v[32:35], v[156:159], v[164:167], v[32:35]
	s_waitcnt lgkmcnt(1)
	v_mfma_f32_16x16x32_bf16 v[0:3], v[132:135], v[168:171], v[0:3]
	v_mfma_f32_16x16x32_bf16 v[4:7], v[140:143], v[168:171], v[4:7]
	v_mfma_f32_16x16x32_bf16 v[44:47], v[148:151], v[168:171], v[44:47]
	v_mfma_f32_16x16x32_bf16 v[40:43], v[156:159], v[168:171], v[40:43]
	s_waitcnt lgkmcnt(0)
	v_mfma_f32_16x16x32_bf16 v[28:31], v[132:135], v[172:175], v[28:31]
	v_mfma_f32_16x16x32_bf16 v[20:23], v[140:143], v[172:175], v[20:23]
	v_mfma_f32_16x16x32_bf16 v[16:19], v[148:151], v[172:175], v[16:19]
	v_mfma_f32_16x16x32_bf16 v[60:63], v[156:159], v[172:175], v[60:63]
	s_waitcnt vmcnt(0) lgkmcnt(0)
	s_barrier
	ds_read_b128 v[128:131], v241 offset:0
	ds_read_b128 v[136:139], v241 offset:2048
	ds_read_b128 v[144:147], v241 offset:4096
	ds_read_b128 v[152:155], v241 offset:6144
	ds_read_b128 v[132:135], v242 offset:0
	ds_read_b128 v[140:143], v242 offset:2048
	ds_read_b128 v[148:151], v242 offset:4096
	ds_read_b128 v[156:159], v242 offset:6144
	s_waitcnt lgkmcnt(0)
	s_barrier
	s_add_u32 m0, s4, 65536
	ds_read_b128 v[160:163], v243 offset:32768
	global_load_lds_dwordx4 v226, s[100:101]
	s_add_u32 m0, s4, 69632
	ds_read_b128 v[164:167], v243 offset:34816
	global_load_lds_dwordx4 v227, s[100:101]
	s_add_u32 m0, s4, 73728
	ds_read_b128 v[168:171], v243 offset:36864
	global_load_lds_dwordx4 v248, s[100:101]
	s_add_u32 m0, s4, 77824
	ds_read_b128 v[172:175], v243 offset:38912
	global_load_lds_dwordx4 v249, s[100:101]
	s_add_u32 m0, s4, 0
	s_nop 0
	global_load_lds_dwordx4 v226, s[98:99]
	s_add_u32 m0, s4, 4096
	s_nop 0
	global_load_lds_dwordx4 v227, s[98:99]
	s_add_u32 m0, s4, 8192
	s_nop 0
	global_load_lds_dwordx4 v248, s[98:99]
	s_add_u32 m0, s4, 12288
	s_nop 0
	global_load_lds_dwordx4 v249, s[98:99]
	s_add_u32 m0, s4, 16384
	s_nop 0
	global_load_lds_dwordx4 v247, s[98:99]
	s_add_u32 m0, s4, 20480
	s_nop 0
	global_load_lds_dwordx4 v244, s[98:99]
	s_add_u32 m0, s4, 24576
	s_nop 0
	global_load_lds_dwordx4 v245, s[98:99]
	s_add_u32 m0, s4, 28672
	s_nop 0
	global_load_lds_dwordx4 v246, s[98:99]
	s_add_u32 s98, s98, 0x80
	s_addc_u32 s99, s99, 0
	s_add_u32 s100, s100, 0x80
	s_addc_u32 s101, s101, 0
	s_waitcnt lgkmcnt(3)
	v_mfma_f32_16x16x32_bf16 v[124:127], v[128:131], v[160:163], v[124:127]
	ds_read_b128 v[176:179], v243 offset:40960
	v_mfma_f32_16x16x32_bf16 v[120:123], v[136:139], v[160:163], v[120:123]
	v_mfma_f32_16x16x32_bf16 v[116:119], v[144:147], v[160:163], v[116:119]
	v_mfma_f32_16x16x32_bf16 v[112:115], v[152:155], v[160:163], v[112:115]
	s_waitcnt lgkmcnt(3)
	v_mfma_f32_16x16x32_bf16 v[108:111], v[128:131], v[164:167], v[108:111]
	ds_read_b128 v[180:183], v243 offset:43008
	v_mfma_f32_16x16x32_bf16 v[104:107], v[136:139], v[164:167], v[104:107]
	v_mfma_f32_16x16x32_bf16 v[100:103], v[144:147], v[164:167], v[100:103]
	v_mfma_f32_16x16x32_bf16 v[96:99], v[152:155], v[164:167], v[96:99]
	s_waitcnt lgkmcnt(3)
	v_mfma_f32_16x16x32_bf16 v[92:95], v[128:131], v[168:171], v[92:95]
	ds_read_b128 v[160:163], v243 offset:45056
	v_mfma_f32_16x16x32_bf16 v[88:91], v[136:139], v[168:171], v[88:91]
	v_mfma_f32_16x16x32_bf16 v[84:87], v[144:147], v[168:171], v[84:87]
	v_mfma_f32_16x16x32_bf16 v[80:83], v[152:155], v[168:171], v[80:83]
	s_waitcnt lgkmcnt(3)
	v_mfma_f32_16x16x32_bf16 v[76:79], v[128:131], v[172:175], v[76:79]
	ds_read_b128 v[164:167], v243 offset:47104
	v_mfma_f32_16x16x32_bf16 v[64:67], v[136:139], v[172:175], v[64:67]
	v_mfma_f32_16x16x32_bf16 v[72:75], v[144:147], v[172:175], v[72:75]
	v_mfma_f32_16x16x32_bf16 v[68:71], v[152:155], v[172:175], v[68:71]
	s_waitcnt lgkmcnt(3)
	v_mfma_f32_16x16x32_bf16 v[48:51], v[128:131], v[176:179], v[48:51]
	ds_read_b128 v[168:171], v240 offset:32768
	v_mfma_f32_16x16x32_bf16 v[52:55], v[136:139], v[176:179], v[52:55]
	v_mfma_f32_16x16x32_bf16 v[56:59], v[144:147], v[176:179], v[56:59]
	v_mfma_f32_16x16x32_bf16 v[36:39], v[152:155], v[176:179], v[36:39]
	s_waitcnt lgkmcnt(3)
	v_mfma_f32_16x16x32_bf16 v[8:11], v[128:131], v[180:183], v[8:11]
	ds_read_b128 v[172:175], v240 offset:34816
	v_mfma_f32_16x16x32_bf16 v[12:15], v[136:139], v[180:183], v[12:15]
	v_mfma_f32_16x16x32_bf16 v[24:27], v[144:147], v[180:183], v[24:27]
	v_mfma_f32_16x16x32_bf16 v[32:35], v[152:155], v[180:183], v[32:35]
	s_waitcnt lgkmcnt(3)
	v_mfma_f32_16x16x32_bf16 v[0:3], v[128:131], v[160:163], v[0:3]
	ds_read_b128 v[176:179], v240 offset:36864
	v_mfma_f32_16x16x32_bf16 v[4:7], v[136:139], v[160:163], v[4:7]
	v_mfma_f32_16x16x32_bf16 v[44:47], v[144:147], v[160:163], v[44:47]
	v_mfma_f32_16x16x32_bf16 v[40:43], v[152:155], v[160:163], v[40:43]
	s_waitcnt lgkmcnt(3)
	v_mfma_f32_16x16x32_bf16 v[28:31], v[128:131], v[164:167], v[28:31]
	ds_read_b128 v[180:183], v240 offset:38912
	v_mfma_f32_16x16x32_bf16 v[20:23], v[136:139], v[164:167], v[20:23]
	v_mfma_f32_16x16x32_bf16 v[16:19], v[144:147], v[164:167], v[16:19]
	v_mfma_f32_16x16x32_bf16 v[60:63], v[152:155], v[164:167], v[60:63]
	s_waitcnt lgkmcnt(3)
	v_mfma_f32_16x16x32_bf16 v[124:127], v[132:135], v[168:171], v[124:127]
	ds_read_b128 v[160:163], v240 offset:40960
	v_mfma_f32_16x16x32_bf16 v[120:123], v[140:143], v[168:171], v[120:123]
	v_mfma_f32_16x16x32_bf16 v[116:119], v[148:151], v[168:171], v[116:119]
	v_mfma_f32_16x16x32_bf16 v[112:115], v[156:159], v[168:171], v[112:115]
	s_waitcnt lgkmcnt(3)
	v_mfma_f32_16x16x32_bf16 v[108:111], v[132:135], v[172:175], v[108:111]
	ds_read_b128 v[164:167], v240 offset:43008
	v_mfma_f32_16x16x32_bf16 v[104:107], v[140:143], v[172:175], v[104:107]
	v_mfma_f32_16x16x32_bf16 v[100:103], v[148:151], v[172:175], v[100:103]
	v_mfma_f32_16x16x32_bf16 v[96:99], v[156:159], v[172:175], v[96:99]
	s_waitcnt lgkmcnt(3)
	v_mfma_f32_16x16x32_bf16 v[92:95], v[132:135], v[176:179], v[92:95]
	ds_read_b128 v[168:171], v240 offset:45056
	v_mfma_f32_16x16x32_bf16 v[88:91], v[140:143], v[176:179], v[88:91]
	v_mfma_f32_16x16x32_bf16 v[84:87], v[148:151], v[176:179], v[84:87]
	v_mfma_f32_16x16x32_bf16 v[80:83], v[156:159], v[176:179], v[80:83]
	s_waitcnt lgkmcnt(3)
	v_mfma_f32_16x16x32_bf16 v[76:79], v[132:135], v[180:183], v[76:79]
	ds_read_b128 v[172:175], v240 offset:47104
	v_mfma_f32_16x16x32_bf16 v[64:67], v[140:143], v[180:183], v[64:67]
	v_mfma_f32_16x16x32_bf16 v[72:75], v[148:151], v[180:183], v[72:75]
	v_mfma_f32_16x16x32_bf16 v[68:71], v[156:159], v[180:183], v[68:71]
	s_waitcnt lgkmcnt(3)
	v_mfma_f32_16x16x32_bf16 v[48:51], v[132:135], v[160:163], v[48:51]
	v_mfma_f32_16x16x32_bf16 v[52:55], v[140:143], v[160:163], v[52:55]
	v_mfma_f32_16x16x32_bf16 v[56:59], v[148:151], v[160:163], v[56:59]
	v_mfma_f32_16x16x32_bf16 v[36:39], v[156:159], v[160:163], v[36:39]
	s_waitcnt lgkmcnt(2)
	v_mfma_f32_16x16x32_bf16 v[8:11], v[132:135], v[164:167], v[8:11]
	v_mfma_f32_16x16x32_bf16 v[12:15], v[140:143], v[164:167], v[12:15]
	v_mfma_f32_16x16x32_bf16 v[24:27], v[148:151], v[164:167], v[24:27]
	v_mfma_f32_16x16x32_bf16 v[32:35], v[156:159], v[164:167], v[32:35]
	s_waitcnt lgkmcnt(1)
	v_mfma_f32_16x16x32_bf16 v[0:3], v[132:135], v[168:171], v[0:3]
	v_mfma_f32_16x16x32_bf16 v[4:7], v[140:143], v[168:171], v[4:7]
	v_mfma_f32_16x16x32_bf16 v[44:47], v[148:151], v[168:171], v[44:47]
	v_mfma_f32_16x16x32_bf16 v[40:43], v[156:159], v[168:171], v[40:43]
	s_waitcnt lgkmcnt(0)
	v_mfma_f32_16x16x32_bf16 v[28:31], v[132:135], v[172:175], v[28:31]
	v_mfma_f32_16x16x32_bf16 v[20:23], v[140:143], v[172:175], v[20:23]
	v_mfma_f32_16x16x32_bf16 v[16:19], v[148:151], v[172:175], v[16:19]
	v_mfma_f32_16x16x32_bf16 v[60:63], v[156:159], v[172:175], v[60:63]
	s_sub_u32 s5, s5, 1
	s_cmp_lg_u32 s5, 0
	s_cbranch_scc1 .Lg8p2_loop
	s_waitcnt vmcnt(0) lgkmcnt(0)
	s_barrier
	ds_read_b128 v[128:131], v241 offset:0
	ds_read_b128 v[136:139], v241 offset:2048
	ds_read_b128 v[144:147], v241 offset:4096
	ds_read_b128 v[152:155], v241 offset:6144
	ds_read_b128 v[132:135], v242 offset:0
	ds_read_b128 v[140:143], v242 offset:2048
	ds_read_b128 v[148:151], v242 offset:4096
	ds_read_b128 v[156:159], v242 offset:6144
	s_waitcnt lgkmcnt(0)
	s_barrier
	s_add_u32 m0, s4, 65536
	ds_read_b128 v[160:163], v243 offset:0
	global_load_lds_dwordx4 v226, s[100:101]
	s_add_u32 m0, s4, 69632
	ds_read_b128 v[164:167], v243 offset:2048
	global_load_lds_dwordx4 v227, s[100:101]
	s_add_u32 m0, s4, 73728
	ds_read_b128 v[168:171], v243 offset:4096
	global_load_lds_dwordx4 v248, s[100:101]
	s_add_u32 m0, s4, 77824
	ds_read_b128 v[172:175], v243 offset:6144
	global_load_lds_dwordx4 v249, s[100:101]
	s_add_u32 m0, s4, 32768
	s_nop 0
	global_load_lds_dwordx4 v226, s[98:99]
	s_add_u32 m0, s4, 36864
	s_nop 0
	global_load_lds_dwordx4 v227, s[98:99]
	s_add_u32 m0, s4, 40960
	s_nop 0
	global_load_lds_dwordx4 v248, s[98:99]
	s_add_u32 m0, s4, 45056
	s_nop 0
	global_load_lds_dwordx4 v249, s[98:99]
	s_add_u32 m0, s4, 49152
	s_nop 0
	global_load_lds_dwordx4 v247, s[98:99]
	s_add_u32 m0, s4, 53248
	s_nop 0
	global_load_lds_dwordx4 v244, s[98:99]
	s_add_u32 m0, s4, 57344
	s_nop 0
	global_load_lds_dwordx4 v245, s[98:99]
	s_add_u32 m0, s4, 61440
	s_nop 0
	global_load_lds_dwordx4 v246, s[98:99]
	s_add_u32 s98, s98, 0x80
	s_addc_u32 s99, s99, 0
	s_add_u32 s100, s100, 0x80
	s_addc_u32 s101, s101, 0
	s_waitcnt lgkmcnt(3)
	v_mfma_f32_16x16x32_bf16 v[124:127], v[128:131], v[160:163], v[124:127]
	ds_read_b128 v[176:179], v243 offset:8192
	v_mfma_f32_16x16x32_bf16 v[120:123], v[136:139], v[160:163], v[120:123]
	v_mfma_f32_16x16x32_bf16 v[116:119], v[144:147], v[160:163], v[116:119]
	v_mfma_f32_16x16x32_bf16 v[112:115], v[152:155], v[160:163], v[112:115]
	s_waitcnt lgkmcnt(3)
	v_mfma_f32_16x16x32_bf16 v[108:111], v[128:131], v[164:167], v[108:111]
	ds_read_b128 v[180:183], v243 offset:10240
	v_mfma_f32_16x16x32_bf16 v[104:107], v[136:139], v[164:167], v[104:107]
	v_mfma_f32_16x16x32_bf16 v[100:103], v[144:147], v[164:167], v[100:103]
	v_mfma_f32_16x16x32_bf16 v[96:99], v[152:155], v[164:167], v[96:99]
	s_waitcnt lgkmcnt(3)
	v_mfma_f32_16x16x32_bf16 v[92:95], v[128:131], v[168:171], v[92:95]
	ds_read_b128 v[160:163], v243 offset:12288
	v_mfma_f32_16x16x32_bf16 v[88:91], v[136:139], v[168:171], v[88:91]
	v_mfma_f32_16x16x32_bf16 v[84:87], v[144:147], v[168:171], v[84:87]
	v_mfma_f32_16x16x32_bf16 v[80:83], v[152:155], v[168:171], v[80:83]
	s_waitcnt lgkmcnt(3)
	v_mfma_f32_16x16x32_bf16 v[76:79], v[128:131], v[172:175], v[76:79]
	ds_read_b128 v[164:167], v243 offset:14336
	v_mfma_f32_16x16x32_bf16 v[64:67], v[136:139], v[172:175], v[64:67]
	v_mfma_f32_16x16x32_bf16 v[72:75], v[144:147], v[172:175], v[72:75]
	v_mfma_f32_16x16x32_bf16 v[68:71], v[152:155], v[172:175], v[68:71]
	s_waitcnt lgkmcnt(3)
	v_mfma_f32_16x16x32_bf16 v[48:51], v[128:131], v[176:179], v[48:51]
	ds_read_b128 v[168:171], v240 offset:0
	v_mfma_f32_16x16x32_bf16 v[52:55], v[136:139], v[176:179], v[52:55]
	v_mfma_f32_16x16x32_bf16 v[56:59], v[144:147], v[176:179], v[56:59]
	v_mfma_f32_16x16x32_bf16 v[36:39], v[152:155], v[176:179], v[36:39]
	s_waitcnt lgkmcnt(3)
	v_mfma_f32_16x16x32_bf16 v[8:11], v[128:131], v[180:183], v[8:11]
	ds_read_b128 v[172:175], v240 offset:2048
	v_mfma_f32_16x16x32_bf16 v[12:15], v[136:139], v[180:183], v[12:15]
	v_mfma_f32_16x16x32_bf16 v[24:27], v[144:147], v[180:183], v[24:27]
	v_mfma_f32_16x16x32_bf16 v[32:35], v[152:155], v[180:183], v[32:35]
	s_waitcnt lgkmcnt(3)
	v_mfma_f32_16x16x32_bf16 v[0:3], v[128:131], v[160:163], v[0:3]
	ds_read_b128 v[176:179], v240 offset:4096
	v_mfma_f32_16x16x32_bf16 v[4:7], v[136:139], v[160:163], v[4:7]
	v_mfma_f32_16x16x32_bf16 v[44:47], v[144:147], v[160:163], v[44:47]
	v_mfma_f32_16x16x32_bf16 v[40:43], v[152:155], v[160:163], v[40:43]
	s_waitcnt lgkmcnt(3)
	v_mfma_f32_16x16x32_bf16 v[28:31], v[128:131], v[164:167], v[28:31]
	ds_read_b128 v[180:183], v240 offset:6144
	v_mfma_f32_16x16x32_bf16 v[20:23], v[136:139], v[164:167], v[20:23]
	v_mfma_f32_16x16x32_bf16 v[16:19], v[144:147], v[164:167], v[16:19]
	v_mfma_f32_16x16x32_bf16 v[60:63], v[152:155], v[164:167], v[60:63]
	s_waitcnt lgkmcnt(3)
	v_mfma_f32_16x16x32_bf16 v[124:127], v[132:135], v[168:171], v[124:127]
	ds_read_b128 v[160:163], v240 offset:8192
	v_mfma_f32_16x16x32_bf16 v[120:123], v[140:143], v[168:171], v[120:123]
	v_mfma_f32_16x16x32_bf16 v[116:119], v[148:151], v[168:171], v[116:119]
	v_mfma_f32_16x16x32_bf16 v[112:115], v[156:159], v[168:171], v[112:115]
	s_waitcnt lgkmcnt(3)
	v_mfma_f32_16x16x32_bf16 v[108:111], v[132:135], v[172:175], v[108:111]
	ds_read_b128 v[164:167], v240 offset:10240
	v_mfma_f32_16x16x32_bf16 v[104:107], v[140:143], v[172:175], v[104:107]
	v_mfma_f32_16x16x32_bf16 v[100:103], v[148:151], v[172:175], v[100:103]
	v_mfma_f32_16x16x32_bf16 v[96:99], v[156:159], v[172:175], v[96:99]
	s_waitcnt lgkmcnt(3)
	v_mfma_f32_16x16x32_bf16 v[92:95], v[132:135], v[176:179], v[92:95]
	ds_read_b128 v[168:171], v240 offset:12288
	v_mfma_f32_16x16x32_bf16 v[88:91], v[140:143], v[176:179], v[88:91]
	v_mfma_f32_16x16x32_bf16 v[84:87], v[148:151], v[176:179], v[84:87]
	v_mfma_f32_16x16x32_bf16 v[80:83], v[156:159], v[176:179], v[80:83]
	s_waitcnt lgkmcnt(3)
	v_mfma_f32_16x16x32_bf16 v[76:79], v[132:135], v[180:183], v[76:79]
	ds_read_b128 v[172:175], v240 offset:14336
	v_mfma_f32_16x16x32_bf16 v[64:67], v[140:143], v[180:183], v[64:67]
	v_mfma_f32_16x16x32_bf16 v[72:75], v[148:151], v[180:183], v[72:75]
	v_mfma_f32_16x16x32_bf16 v[68:71], v[156:159], v[180:183], v[68:71]
	s_waitcnt lgkmcnt(3)
	v_mfma_f32_16x16x32_bf16 v[48:51], v[132:135], v[160:163], v[48:51]
	v_mfma_f32_16x16x32_bf16 v[52:55], v[140:143], v[160:163], v[52:55]
	v_mfma_f32_16x16x32_bf16 v[56:59], v[148:151], v[160:163], v[56:59]
	v_mfma_f32_16x16x32_bf16 v[36:39], v[156:159], v[160:163], v[36:39]
	s_waitcnt lgkmcnt(2)
	v_mfma_f32_16x16x32_bf16 v[8:11], v[132:135], v[164:167], v[8:11]
	v_mfma_f32_16x16x32_bf16 v[12:15], v[140:143], v[164:167], v[12:15]
	v_mfma_f32_16x16x32_bf16 v[24:27], v[148:151], v[164:167], v[24:27]
	v_mfma_f32_16x16x32_bf16 v[32:35], v[156:159], v[164:167], v[32:35]
	s_waitcnt lgkmcnt(1)
	v_mfma_f32_16x16x32_bf16 v[0:3], v[132:135], v[168:171], v[0:3]
	v_mfma_f32_16x16x32_bf16 v[4:7], v[140:143], v[168:171], v[4:7]
	v_mfma_f32_16x16x32_bf16 v[44:47], v[148:151], v[168:171], v[44:47]
	v_mfma_f32_16x16x32_bf16 v[40:43], v[156:159], v[168:171], v[40:43]
	s_waitcnt lgkmcnt(0)
	v_mfma_f32_16x16x32_bf16 v[28:31], v[132:135], v[172:175], v[28:31]
	v_mfma_f32_16x16x32_bf16 v[20:23], v[140:143], v[172:175], v[20:23]
	v_mfma_f32_16x16x32_bf16 v[16:19], v[148:151], v[172:175], v[16:19]
	v_mfma_f32_16x16x32_bf16 v[60:63], v[156:159], v[172:175], v[60:63]
	s_waitcnt vmcnt(0) lgkmcnt(0)
	s_barrier
	ds_read_b128 v[128:131], v241 offset:0
	ds_read_b128 v[136:139], v241 offset:2048
	ds_read_b128 v[144:147], v241 offset:4096
	ds_read_b128 v[152:155], v241 offset:6144
	ds_read_b128 v[132:135], v242 offset:0
	ds_read_b128 v[140:143], v242 offset:2048
	ds_read_b128 v[148:151], v242 offset:4096
	ds_read_b128 v[156:159], v242 offset:6144
	ds_read_b128 v[160:163], v243 offset:32768
	ds_read_b128 v[164:167], v243 offset:34816
	ds_read_b128 v[168:171], v243 offset:36864
	ds_read_b128 v[172:175], v243 offset:38912
	s_waitcnt lgkmcnt(4)
	s_waitcnt lgkmcnt(3)
	v_mfma_f32_16x16x32_bf16 v[124:127], v[128:131], v[160:163], v[124:127]
	ds_read_b128 v[176:179], v243 offset:40960
	v_mfma_f32_16x16x32_bf16 v[120:123], v[136:139], v[160:163], v[120:123]
	v_mfma_f32_16x16x32_bf16 v[116:119], v[144:147], v[160:163], v[116:119]
	v_mfma_f32_16x16x32_bf16 v[112:115], v[152:155], v[160:163], v[112:115]
	s_waitcnt lgkmcnt(3)
	v_mfma_f32_16x16x32_bf16 v[108:111], v[128:131], v[164:167], v[108:111]
	ds_read_b128 v[180:183], v243 offset:43008
	v_mfma_f32_16x16x32_bf16 v[104:107], v[136:139], v[164:167], v[104:107]
	v_mfma_f32_16x16x32_bf16 v[100:103], v[144:147], v[164:167], v[100:103]
	v_mfma_f32_16x16x32_bf16 v[96:99], v[152:155], v[164:167], v[96:99]
	s_waitcnt lgkmcnt(3)
	v_mfma_f32_16x16x32_bf16 v[92:95], v[128:131], v[168:171], v[92:95]
	ds_read_b128 v[160:163], v243 offset:45056
	v_mfma_f32_16x16x32_bf16 v[88:91], v[136:139], v[168:171], v[88:91]
	v_mfma_f32_16x16x32_bf16 v[84:87], v[144:147], v[168:171], v[84:87]
	v_mfma_f32_16x16x32_bf16 v[80:83], v[152:155], v[168:171], v[80:83]
	s_waitcnt lgkmcnt(3)
	v_mfma_f32_16x16x32_bf16 v[76:79], v[128:131], v[172:175], v[76:79]
	ds_read_b128 v[164:167], v243 offset:47104
	v_mfma_f32_16x16x32_bf16 v[64:67], v[136:139], v[172:175], v[64:67]
	v_mfma_f32_16x16x32_bf16 v[72:75], v[144:147], v[172:175], v[72:75]
	v_mfma_f32_16x16x32_bf16 v[68:71], v[152:155], v[172:175], v[68:71]
	s_waitcnt lgkmcnt(3)
	v_mfma_f32_16x16x32_bf16 v[48:51], v[128:131], v[176:179], v[48:51]
	ds_read_b128 v[168:171], v240 offset:32768
	v_mfma_f32_16x16x32_bf16 v[52:55], v[136:139], v[176:179], v[52:55]
	v_mfma_f32_16x16x32_bf16 v[56:59], v[144:147], v[176:179], v[56:59]
	v_mfma_f32_16x16x32_bf16 v[36:39], v[152:155], v[176:179], v[36:39]
	s_waitcnt lgkmcnt(3)
	v_mfma_f32_16x16x32_bf16 v[8:11], v[128:131], v[180:183], v[8:11]
	ds_read_b128 v[172:175], v240 offset:34816
	v_mfma_f32_16x16x32_bf16 v[12:15], v[136:139], v[180:183], v[12:15]
	v_mfma_f32_16x16x32_bf16 v[24:27], v[144:147], v[180:183], v[24:27]
	v_mfma_f32_16x16x32_bf16 v[32:35], v[152:155], v[180:183], v[32:35]
	s_waitcnt lgkmcnt(3)
	v_mfma_f32_16x16x32_bf16 v[0:3], v[128:131], v[160:163], v[0:3]
	ds_read_b128 v[176:179], v240 offset:36864
	v_mfma_f32_16x16x32_bf16 v[4:7], v[136:139], v[160:163], v[4:7]
	v_mfma_f32_16x16x32_bf16 v[44:47], v[144:147], v[160:163], v[44:47]
	v_mfma_f32_16x16x32_bf16 v[40:43], v[152:155], v[160:163], v[40:43]
	s_waitcnt lgkmcnt(3)
	v_mfma_f32_16x16x32_bf16 v[28:31], v[128:131], v[164:167], v[28:31]
	ds_read_b128 v[180:183], v240 offset:38912
	v_mfma_f32_16x16x32_bf16 v[20:23], v[136:139], v[164:167], v[20:23]
	v_mfma_f32_16x16x32_bf16 v[16:19], v[144:147], v[164:167], v[16:19]
	v_mfma_f32_16x16x32_bf16 v[60:63], v[152:155], v[164:167], v[60:63]
	s_waitcnt lgkmcnt(3)
	v_mfma_f32_16x16x32_bf16 v[124:127], v[132:135], v[168:171], v[124:127]
	ds_read_b128 v[160:163], v240 offset:40960
	v_mfma_f32_16x16x32_bf16 v[120:123], v[140:143], v[168:171], v[120:123]
	v_mfma_f32_16x16x32_bf16 v[116:119], v[148:151], v[168:171], v[116:119]
	v_mfma_f32_16x16x32_bf16 v[112:115], v[156:159], v[168:171], v[112:115]
	s_waitcnt lgkmcnt(3)
	v_mfma_f32_16x16x32_bf16 v[108:111], v[132:135], v[172:175], v[108:111]
	ds_read_b128 v[164:167], v240 offset:43008
	v_mfma_f32_16x16x32_bf16 v[104:107], v[140:143], v[172:175], v[104:107]
	v_mfma_f32_16x16x32_bf16 v[100:103], v[148:151], v[172:175], v[100:103]
	v_mfma_f32_16x16x32_bf16 v[96:99], v[156:159], v[172:175], v[96:99]
	s_waitcnt lgkmcnt(3)
	v_mfma_f32_16x16x32_bf16 v[92:95], v[132:135], v[176:179], v[92:95]
	ds_read_b128 v[168:171], v240 offset:45056
	v_mfma_f32_16x16x32_bf16 v[88:91], v[140:143], v[176:179], v[88:91]
	v_mfma_f32_16x16x32_bf16 v[84:87], v[148:151], v[176:179], v[84:87]
	v_mfma_f32_16x16x32_bf16 v[80:83], v[156:159], v[176:179], v[80:83]
	s_waitcnt lgkmcnt(3)
	v_mfma_f32_16x16x32_bf16 v[76:79], v[132:135], v[180:183], v[76:79]
	ds_read_b128 v[172:175], v240 offset:47104
	v_mfma_f32_16x16x32_bf16 v[64:67], v[140:143], v[180:183], v[64:67]
	v_mfma_f32_16x16x32_bf16 v[72:75], v[148:151], v[180:183], v[72:75]
	v_mfma_f32_16x16x32_bf16 v[68:71], v[156:159], v[180:183], v[68:71]
	s_waitcnt lgkmcnt(3)
	v_mfma_f32_16x16x32_bf16 v[48:51], v[132:135], v[160:163], v[48:51]
	v_mfma_f32_16x16x32_bf16 v[52:55], v[140:143], v[160:163], v[52:55]
	v_mfma_f32_16x16x32_bf16 v[56:59], v[148:151], v[160:163], v[56:59]
	v_mfma_f32_16x16x32_bf16 v[36:39], v[156:159], v[160:163], v[36:39]
	s_waitcnt lgkmcnt(2)
	v_mfma_f32_16x16x32_bf16 v[8:11], v[132:135], v[164:167], v[8:11]
	v_mfma_f32_16x16x32_bf16 v[12:15], v[140:143], v[164:167], v[12:15]
	v_mfma_f32_16x16x32_bf16 v[24:27], v[148:151], v[164:167], v[24:27]
	v_mfma_f32_16x16x32_bf16 v[32:35], v[156:159], v[164:167], v[32:35]
	s_waitcnt lgkmcnt(1)
	v_mfma_f32_16x16x32_bf16 v[0:3], v[132:135], v[168:171], v[0:3]
	v_mfma_f32_16x16x32_bf16 v[4:7], v[140:143], v[168:171], v[4:7]
	v_mfma_f32_16x16x32_bf16 v[44:47], v[148:151], v[168:171], v[44:47]
	v_mfma_f32_16x16x32_bf16 v[40:43], v[156:159], v[168:171], v[40:43]
	s_waitcnt lgkmcnt(0)
	v_mfma_f32_16x16x32_bf16 v[28:31], v[132:135], v[172:175], v[28:31]
	v_mfma_f32_16x16x32_bf16 v[20:23], v[140:143], v[172:175], v[20:23]
	v_mfma_f32_16x16x32_bf16 v[16:19], v[148:151], v[172:175], v[16:19]
	v_mfma_f32_16x16x32_bf16 v[60:63], v[156:159], v[172:175], v[60:63]
	s_nop 7
	s_nop 7
	s_barrier
	ds_write_b64 v194, v[192:193]
	v_mov_b32_e32 v152, v120
	v_mov_b32_e32 v153, v121
	v_mov_b32_e32 v154, v122
	v_mov_b32_e32 v155, v123
	s_movk_i32 s4, 0xc00
	v_mov_b32_e32 v160, v116
	v_mov_b32_e32 v161, v117
	v_mov_b32_e32 v162, v118
	v_mov_b32_e32 v163, v119
	v_mov_b32_e32 v192, v68
	v_mov_b32_e32 v193, v69
	v_mov_b32_e32 v194, v70
	v_mov_b32_e32 v195, v71
	v_mov_b32_e32 v230, v56
	v_mov_b32_e32 v231, v57
	v_mov_b32_e32 v232, v58
	v_mov_b32_e32 v233, v59
	v_mov_b32_e32 v246, v40
	v_mov_b32_e32 v247, v41
	v_mov_b32_e32 v248, v42
	v_mov_b32_e32 v249, v43
	v_mov_b32_e32 v180, v72
	v_mov_b32_e32 v181, v73
	v_mov_b32_e32 v182, v74
	v_mov_b32_e32 v183, v75
	v_mov_b32_e32 v242, v44
	v_mov_b32_e32 v243, v45
	v_mov_b32_e32 v244, v46
	v_mov_b32_e32 v245, v47
	v_mov_b32_e32 v208, v28
	v_mov_b32_e32 v209, v29
	v_mov_b32_e32 v210, v30
	v_mov_b32_e32 v211, v31
	v_mov_b32_e32 v148, v20
	v_mov_b32_e32 v149, v21
	v_mov_b32_e32 v150, v22
	v_mov_b32_e32 v151, v23
	v_mov_b32_e32 v156, v16
	v_mov_b32_e32 v157, v17
	v_mov_b32_e32 v158, v18
	v_mov_b32_e32 v159, v19
	v_mov_b32_e32 v164, v60
	v_mov_b32_e32 v165, v61
	v_mov_b32_e32 v166, v62
	v_mov_b32_e32 v167, v63
	v_mov_b32_e32 v28, v0
	v_mov_b32_e32 v29, v1
	v_mov_b32_e32 v30, v2
	v_mov_b32_e32 v31, v3
	v_or_b32_e32 v0, s16, v199
	v_mov_b32_e32 v140, v124
	v_mov_b32_e32 v141, v125
	v_mov_b32_e32 v142, v126
	v_mov_b32_e32 v143, v127
	v_cmp_ne_u32_e64 s[4:5], s4, v0
	v_mov_b32_e32 v128, v152
	v_mov_b32_e32 v129, v153
	v_mov_b32_e32 v130, v154
	v_mov_b32_e32 v131, v155
	v_mov_b32_e32 v124, v160
	v_mov_b32_e32 v125, v161
	v_mov_b32_e32 v126, v162
	v_mov_b32_e32 v127, v163
	v_mov_b32_e32 v72, v64
	v_mov_b32_e32 v73, v65
	v_mov_b32_e32 v74, v66
	v_mov_b32_e32 v75, v67
	v_mov_b32_e32 v68, v180
	v_mov_b32_e32 v69, v181
	v_mov_b32_e32 v70, v182
	v_mov_b32_e32 v71, v183
	v_mov_b32_e32 v64, v192
	v_mov_b32_e32 v65, v193
	v_mov_b32_e32 v66, v194
	v_mov_b32_e32 v67, v195
	v_mov_b32_e32 v60, v48
	v_mov_b32_e32 v61, v49
	v_mov_b32_e32 v62, v50
	v_mov_b32_e32 v63, v51
	v_mov_b32_e32 v56, v52
	v_mov_b32_e32 v57, v53
	v_mov_b32_e32 v58, v54
	v_mov_b32_e32 v59, v55
	v_mov_b32_e32 v52, v230
	v_mov_b32_e32 v53, v231
	v_mov_b32_e32 v54, v232
	v_mov_b32_e32 v55, v233
	v_mov_b32_e32 v48, v36
	v_mov_b32_e32 v49, v37
	v_mov_b32_e32 v50, v38
	v_mov_b32_e32 v51, v39
	v_mov_b32_e32 v44, v8
	v_mov_b32_e32 v45, v9
	v_mov_b32_e32 v46, v10
	v_mov_b32_e32 v47, v11
	v_mov_b32_e32 v40, v12
	v_mov_b32_e32 v41, v13
	v_mov_b32_e32 v42, v14
	v_mov_b32_e32 v43, v15
	v_mov_b32_e32 v36, v24
	v_mov_b32_e32 v37, v25
	v_mov_b32_e32 v38, v26
	v_mov_b32_e32 v39, v27
	v_mov_b32_e32 v24, v4
	v_mov_b32_e32 v25, v5
	v_mov_b32_e32 v26, v6
	v_mov_b32_e32 v27, v7
	v_mov_b32_e32 v20, v242
	v_mov_b32_e32 v21, v243
	v_mov_b32_e32 v22, v244
	v_mov_b32_e32 v23, v245
	v_mov_b32_e32 v12, v246
	v_mov_b32_e32 v13, v247
	v_mov_b32_e32 v14, v248
	v_mov_b32_e32 v15, v249
	v_mov_b32_e32 v16, v208
	v_mov_b32_e32 v17, v209
	v_mov_b32_e32 v18, v210
	v_mov_b32_e32 v19, v211
	v_mov_b32_e32 v8, v148
	v_mov_b32_e32 v9, v149
	v_mov_b32_e32 v10, v150
	v_mov_b32_e32 v11, v151
	v_mov_b32_e32 v4, v156
	v_mov_b32_e32 v5, v157
	v_mov_b32_e32 v6, v158
	v_mov_b32_e32 v7, v159
	v_mov_b32_e32 v0, v164
	v_mov_b32_e32 v1, v165
	v_mov_b32_e32 v2, v166
	v_mov_b32_e32 v3, v167
	s_and_saveexec_b64 s[8:9], s[4:5]
	s_xor_b64 s[8:9], exec, s[8:9]
	s_or_saveexec_b64 s[8:9], s[8:9]
	v_add_u32_e32 v120, s6, v197
	v_or_b32_e32 v116, v120, v198
	v_lshlrev_b32_e32 v116, 6, v116
	v_ashrrev_i32_e32 v117, 31, v116
	v_or_b32_e32 v184, s16, v200
	v_lshl_add_u64 v[116:117], v[116:117], 2, s[12:13]
	s_xor_b64 exec, exec, s[8:9]
	s_cbranch_execz .LBB0_263
	v_lshl_add_u64 v[118:119], v[184:185], 2, v[116:117]
	v_add_co_u32_e32 v118, vcc, 0xffffd000, v118
	s_nop 1
	v_addc_co_u32_e32 v119, vcc, -1, v119, vcc
	global_store_dwordx4 v[118:119], v[140:143], off

.Lg8p3_loop:
	s_waitcnt vmcnt(0) lgkmcnt(0)
	s_barrier
	ds_read_b128 v[128:131], v240 offset:0
	ds_read_b128 v[136:139], v240 offset:2048
	ds_read_b128 v[144:147], v240 offset:4096
	ds_read_b128 v[152:155], v240 offset:6144
	ds_read_b128 v[132:135], v241 offset:0
	ds_read_b128 v[140:143], v241 offset:2048
	ds_read_b128 v[148:151], v241 offset:4096
	ds_read_b128 v[156:159], v241 offset:6144
	s_waitcnt lgkmcnt(0)
	s_barrier
	s_add_u32 m0, s0, 65536
	ds_read_b128 v[160:163], v246 offset:0
	global_load_lds_dwordx4 v252, s[100:101]
	s_add_u32 m0, s0, 69632
	ds_read_b128 v[164:167], v246 offset:2048
	global_load_lds_dwordx4 v251, s[100:101]
	s_add_u32 m0, s0, 73728
	ds_read_b128 v[168:171], v246 offset:4096
	global_load_lds_dwordx4 v248, s[100:101]
	s_add_u32 m0, s0, 77824
	ds_read_b128 v[172:175], v246 offset:6144
	global_load_lds_dwordx4 v249, s[100:101]
	s_add_u32 m0, s0, 32768
	s_nop 0
	global_load_lds_dwordx4 v252, s[98:99]
	s_add_u32 m0, s0, 36864
	s_nop 0
	global_load_lds_dwordx4 v251, s[98:99]
	s_add_u32 m0, s0, 40960
	s_nop 0
	global_load_lds_dwordx4 v248, s[98:99]
	s_add_u32 m0, s0, 45056
	s_nop 0
	global_load_lds_dwordx4 v249, s[98:99]
	s_add_u32 m0, s0, 49152
	s_nop 0
	global_load_lds_dwordx4 v250, s[98:99]
	s_add_u32 m0, s0, 53248
	s_nop 0
	global_load_lds_dwordx4 v247, s[98:99]
	s_add_u32 m0, s0, 57344
	s_nop 0
	global_load_lds_dwordx4 v244, s[98:99]
	s_add_u32 m0, s0, 61440
	s_nop 0
	global_load_lds_dwordx4 v245, s[98:99]
	s_add_u32 s98, s98, 0x80
	s_addc_u32 s99, s99, 0
	s_add_u32 s100, s100, 0x80
	s_addc_u32 s101, s101, 0
	s_waitcnt lgkmcnt(3)
	v_mfma_f32_16x16x32_bf16 v[120:123], v[128:131], v[160:163], v[120:123]
	ds_read_b128 v[176:179], v246 offset:8192
	v_mfma_f32_16x16x32_bf16 v[116:119], v[136:139], v[160:163], v[116:119]
	v_mfma_f32_16x16x32_bf16 v[112:115], v[144:147], v[160:163], v[112:115]
	v_mfma_f32_16x16x32_bf16 v[108:111], v[152:155], v[160:163], v[108:111]
	s_waitcnt lgkmcnt(3)
	v_mfma_f32_16x16x32_bf16 v[96:99], v[128:131], v[164:167], v[96:99]
	ds_read_b128 v[180:183], v246 offset:10240
	v_mfma_f32_16x16x32_bf16 v[84:87], v[136:139], v[164:167], v[84:87]
	v_mfma_f32_16x16x32_bf16 v[76:79], v[144:147], v[164:167], v[76:79]
	v_mfma_f32_16x16x32_bf16 v[72:75], v[152:155], v[164:167], v[72:75]
	s_waitcnt lgkmcnt(3)
	v_mfma_f32_16x16x32_bf16 v[68:71], v[128:131], v[168:171], v[68:71]
	ds_read_b128 v[160:163], v246 offset:12288
	v_mfma_f32_16x16x32_bf16 v[64:67], v[136:139], v[168:171], v[64:67]
	v_mfma_f32_16x16x32_bf16 v[60:63], v[144:147], v[168:171], v[60:63]
	v_mfma_f32_16x16x32_bf16 v[56:59], v[152:155], v[168:171], v[56:59]
	s_waitcnt lgkmcnt(3)
	v_mfma_f32_16x16x32_bf16 v[28:31], v[128:131], v[172:175], v[28:31]
	ds_read_b128 v[164:167], v246 offset:14336
	v_mfma_f32_16x16x32_bf16 v[4:7], v[136:139], v[172:175], v[4:7]
	v_mfma_f32_16x16x32_bf16 v[24:27], v[144:147], v[172:175], v[24:27]
	v_mfma_f32_16x16x32_bf16 v[20:23], v[152:155], v[172:175], v[20:23]
	s_waitcnt lgkmcnt(3)
	v_mfma_f32_16x16x32_bf16 v[0:3], v[128:131], v[176:179], v[0:3]
	ds_read_b128 v[168:171], v243 offset:0
	v_mfma_f32_16x16x32_bf16 v[8:11], v[136:139], v[176:179], v[8:11]
	v_mfma_f32_16x16x32_bf16 v[16:19], v[144:147], v[176:179], v[16:19]
	v_mfma_f32_16x16x32_bf16 v[36:39], v[152:155], v[176:179], v[36:39]
	s_waitcnt lgkmcnt(3)
	v_mfma_f32_16x16x32_bf16 v[12:15], v[128:131], v[180:183], v[12:15]
	ds_read_b128 v[172:175], v243 offset:2048
	v_mfma_f32_16x16x32_bf16 v[32:35], v[136:139], v[180:183], v[32:35]
	v_mfma_f32_16x16x32_bf16 v[44:47], v[144:147], v[180:183], v[44:47]
	v_mfma_f32_16x16x32_bf16 v[52:55], v[152:155], v[180:183], v[52:55]
	s_waitcnt lgkmcnt(3)
	v_mfma_f32_16x16x32_bf16 v[40:43], v[128:131], v[160:163], v[40:43]
	ds_read_b128 v[176:179], v243 offset:4096
	v_mfma_f32_16x16x32_bf16 v[48:51], v[136:139], v[160:163], v[48:51]
	v_mfma_f32_16x16x32_bf16 v[104:107], v[144:147], v[160:163], v[104:107]
	v_mfma_f32_16x16x32_bf16 v[100:103], v[152:155], v[160:163], v[100:103]
	s_waitcnt lgkmcnt(3)
	v_mfma_f32_16x16x32_bf16 v[92:95], v[128:131], v[164:167], v[92:95]
	ds_read_b128 v[180:183], v243 offset:6144
	v_mfma_f32_16x16x32_bf16 v[88:91], v[136:139], v[164:167], v[88:91]
	v_mfma_f32_16x16x32_bf16 v[80:83], v[144:147], v[164:167], v[80:83]
	v_mfma_f32_16x16x32_bf16 v[124:127], v[152:155], v[164:167], v[124:127]
	s_waitcnt lgkmcnt(3)
	v_mfma_f32_16x16x32_bf16 v[120:123], v[132:135], v[168:171], v[120:123]
	ds_read_b128 v[160:163], v243 offset:8192
	v_mfma_f32_16x16x32_bf16 v[116:119], v[140:143], v[168:171], v[116:119]
	v_mfma_f32_16x16x32_bf16 v[112:115], v[148:151], v[168:171], v[112:115]
	v_mfma_f32_16x16x32_bf16 v[108:111], v[156:159], v[168:171], v[108:111]
	s_waitcnt lgkmcnt(3)
	v_mfma_f32_16x16x32_bf16 v[96:99], v[132:135], v[172:175], v[96:99]
	ds_read_b128 v[164:167], v243 offset:10240
	v_mfma_f32_16x16x32_bf16 v[84:87], v[140:143], v[172:175], v[84:87]
	v_mfma_f32_16x16x32_bf16 v[76:79], v[148:151], v[172:175], v[76:79]
	v_mfma_f32_16x16x32_bf16 v[72:75], v[156:159], v[172:175], v[72:75]
	s_waitcnt lgkmcnt(3)
	v_mfma_f32_16x16x32_bf16 v[68:71], v[132:135], v[176:179], v[68:71]
	ds_read_b128 v[168:171], v243 offset:12288
	v_mfma_f32_16x16x32_bf16 v[64:67], v[140:143], v[176:179], v[64:67]
	v_mfma_f32_16x16x32_bf16 v[60:63], v[148:151], v[176:179], v[60:63]
	v_mfma_f32_16x16x32_bf16 v[56:59], v[156:159], v[176:179], v[56:59]
	s_waitcnt lgkmcnt(3)
	v_mfma_f32_16x16x32_bf16 v[28:31], v[132:135], v[180:183], v[28:31]
	ds_read_b128 v[172:175], v243 offset:14336
	v_mfma_f32_16x16x32_bf16 v[4:7], v[140:143], v[180:183], v[4:7]
	v_mfma_f32_16x16x32_bf16 v[24:27], v[148:151], v[180:183], v[24:27]
	v_mfma_f32_16x16x32_bf16 v[20:23], v[156:159], v[180:183], v[20:23]
	s_waitcnt lgkmcnt(3)
	v_mfma_f32_16x16x32_bf16 v[0:3], v[132:135], v[160:163], v[0:3]
	v_mfma_f32_16x16x32_bf16 v[8:11], v[140:143], v[160:163], v[8:11]
	v_mfma_f32_16x16x32_bf16 v[16:19], v[148:151], v[160:163], v[16:19]
	v_mfma_f32_16x16x32_bf16 v[36:39], v[156:159], v[160:163], v[36:39]
	s_waitcnt lgkmcnt(2)
	v_mfma_f32_16x16x32_bf16 v[12:15], v[132:135], v[164:167], v[12:15]
	v_mfma_f32_16x16x32_bf16 v[32:35], v[140:143], v[164:167], v[32:35]
	v_mfma_f32_16x16x32_bf16 v[44:47], v[148:151], v[164:167], v[44:47]
	v_mfma_f32_16x16x32_bf16 v[52:55], v[156:159], v[164:167], v[52:55]
	s_waitcnt lgkmcnt(1)
	v_mfma_f32_16x16x32_bf16 v[40:43], v[132:135], v[168:171], v[40:43]
	v_mfma_f32_16x16x32_bf16 v[48:51], v[140:143], v[168:171], v[48:51]
	v_mfma_f32_16x16x32_bf16 v[104:107], v[148:151], v[168:171], v[104:107]
	v_mfma_f32_16x16x32_bf16 v[100:103], v[156:159], v[168:171], v[100:103]
	s_waitcnt lgkmcnt(0)
	v_mfma_f32_16x16x32_bf16 v[92:95], v[132:135], v[172:175], v[92:95]
	v_mfma_f32_16x16x32_bf16 v[88:91], v[140:143], v[172:175], v[88:91]
	v_mfma_f32_16x16x32_bf16 v[80:83], v[148:151], v[172:175], v[80:83]
	v_mfma_f32_16x16x32_bf16 v[124:127], v[156:159], v[172:175], v[124:127]
	s_waitcnt vmcnt(0) lgkmcnt(0)
	s_barrier
	ds_read_b128 v[128:131], v240 offset:0
	ds_read_b128 v[136:139], v240 offset:2048
	ds_read_b128 v[144:147], v240 offset:4096
	ds_read_b128 v[152:155], v240 offset:6144
	ds_read_b128 v[132:135], v241 offset:0
	ds_read_b128 v[140:143], v241 offset:2048
	ds_read_b128 v[148:151], v241 offset:4096
	ds_read_b128 v[156:159], v241 offset:6144
	s_waitcnt lgkmcnt(0)
	s_barrier
	s_add_u32 m0, s0, 65536
	ds_read_b128 v[160:163], v246 offset:32768
	global_load_lds_dwordx4 v252, s[100:101]
	s_add_u32 m0, s0, 69632
	ds_read_b128 v[164:167], v246 offset:34816
	global_load_lds_dwordx4 v251, s[100:101]
	s_add_u32 m0, s0, 73728
	ds_read_b128 v[168:171], v246 offset:36864
	global_load_lds_dwordx4 v248, s[100:101]
	s_add_u32 m0, s0, 77824
	ds_read_b128 v[172:175], v246 offset:38912
	global_load_lds_dwordx4 v249, s[100:101]
	s_add_u32 m0, s0, 0
	s_nop 0
	global_load_lds_dwordx4 v252, s[98:99]
	s_add_u32 m0, s0, 4096
	s_nop 0
	global_load_lds_dwordx4 v251, s[98:99]
	s_add_u32 m0, s0, 8192
	s_nop 0
	global_load_lds_dwordx4 v248, s[98:99]
	s_add_u32 m0, s0, 12288
	s_nop 0
	global_load_lds_dwordx4 v249, s[98:99]
	s_add_u32 m0, s0, 16384
	s_nop 0
	global_load_lds_dwordx4 v250, s[98:99]
	s_add_u32 m0, s0, 20480
	s_nop 0
	global_load_lds_dwordx4 v247, s[98:99]
	s_add_u32 m0, s0, 24576
	s_nop 0
	global_load_lds_dwordx4 v244, s[98:99]
	s_add_u32 m0, s0, 28672
	s_nop 0
	global_load_lds_dwordx4 v245, s[98:99]
	s_add_u32 s98, s98, 0x80
	s_addc_u32 s99, s99, 0
	s_add_u32 s100, s100, 0x80
	s_addc_u32 s101, s101, 0
	s_waitcnt lgkmcnt(3)
	v_mfma_f32_16x16x32_bf16 v[120:123], v[128:131], v[160:163], v[120:123]
	ds_read_b128 v[176:179], v246 offset:40960
	v_mfma_f32_16x16x32_bf16 v[116:119], v[136:139], v[160:163], v[116:119]
	v_mfma_f32_16x16x32_bf16 v[112:115], v[144:147], v[160:163], v[112:115]
	v_mfma_f32_16x16x32_bf16 v[108:111], v[152:155], v[160:163], v[108:111]
	s_waitcnt lgkmcnt(3)
	v_mfma_f32_16x16x32_bf16 v[96:99], v[128:131], v[164:167], v[96:99]
	ds_read_b128 v[180:183], v246 offset:43008
	v_mfma_f32_16x16x32_bf16 v[84:87], v[136:139], v[164:167], v[84:87]
	v_mfma_f32_16x16x32_bf16 v[76:79], v[144:147], v[164:167], v[76:79]
	v_mfma_f32_16x16x32_bf16 v[72:75], v[152:155], v[164:167], v[72:75]
	s_waitcnt lgkmcnt(3)
	v_mfma_f32_16x16x32_bf16 v[68:71], v[128:131], v[168:171], v[68:71]
	ds_read_b128 v[160:163], v246 offset:45056
	v_mfma_f32_16x16x32_bf16 v[64:67], v[136:139], v[168:171], v[64:67]
	v_mfma_f32_16x16x32_bf16 v[60:63], v[144:147], v[168:171], v[60:63]
	v_mfma_f32_16x16x32_bf16 v[56:59], v[152:155], v[168:171], v[56:59]
	s_waitcnt lgkmcnt(3)
	v_mfma_f32_16x16x32_bf16 v[28:31], v[128:131], v[172:175], v[28:31]
	ds_read_b128 v[164:167], v246 offset:47104
	v_mfma_f32_16x16x32_bf16 v[4:7], v[136:139], v[172:175], v[4:7]
	v_mfma_f32_16x16x32_bf16 v[24:27], v[144:147], v[172:175], v[24:27]
	v_mfma_f32_16x16x32_bf16 v[20:23], v[152:155], v[172:175], v[20:23]
	s_waitcnt lgkmcnt(3)
	v_mfma_f32_16x16x32_bf16 v[0:3], v[128:131], v[176:179], v[0:3]
	ds_read_b128 v[168:171], v243 offset:32768
	v_mfma_f32_16x16x32_bf16 v[8:11], v[136:139], v[176:179], v[8:11]
	v_mfma_f32_16x16x32_bf16 v[16:19], v[144:147], v[176:179], v[16:19]
	v_mfma_f32_16x16x32_bf16 v[36:39], v[152:155], v[176:179], v[36:39]
	s_waitcnt lgkmcnt(3)
	v_mfma_f32_16x16x32_bf16 v[12:15], v[128:131], v[180:183], v[12:15]
	ds_read_b128 v[172:175], v243 offset:34816
	v_mfma_f32_16x16x32_bf16 v[32:35], v[136:139], v[180:183], v[32:35]
	v_mfma_f32_16x16x32_bf16 v[44:47], v[144:147], v[180:183], v[44:47]
	v_mfma_f32_16x16x32_bf16 v[52:55], v[152:155], v[180:183], v[52:55]
	s_waitcnt lgkmcnt(3)
	v_mfma_f32_16x16x32_bf16 v[40:43], v[128:131], v[160:163], v[40:43]
	ds_read_b128 v[176:179], v243 offset:36864
	v_mfma_f32_16x16x32_bf16 v[48:51], v[136:139], v[160:163], v[48:51]
	v_mfma_f32_16x16x32_bf16 v[104:107], v[144:147], v[160:163], v[104:107]
	v_mfma_f32_16x16x32_bf16 v[100:103], v[152:155], v[160:163], v[100:103]
	s_waitcnt lgkmcnt(3)
	v_mfma_f32_16x16x32_bf16 v[92:95], v[128:131], v[164:167], v[92:95]
	ds_read_b128 v[180:183], v243 offset:38912
	v_mfma_f32_16x16x32_bf16 v[88:91], v[136:139], v[164:167], v[88:91]
	v_mfma_f32_16x16x32_bf16 v[80:83], v[144:147], v[164:167], v[80:83]
	v_mfma_f32_16x16x32_bf16 v[124:127], v[152:155], v[164:167], v[124:127]
	s_waitcnt lgkmcnt(3)
	v_mfma_f32_16x16x32_bf16 v[120:123], v[132:135], v[168:171], v[120:123]
	ds_read_b128 v[160:163], v243 offset:40960
	v_mfma_f32_16x16x32_bf16 v[116:119], v[140:143], v[168:171], v[116:119]
	v_mfma_f32_16x16x32_bf16 v[112:115], v[148:151], v[168:171], v[112:115]
	v_mfma_f32_16x16x32_bf16 v[108:111], v[156:159], v[168:171], v[108:111]
	s_waitcnt lgkmcnt(3)
	v_mfma_f32_16x16x32_bf16 v[96:99], v[132:135], v[172:175], v[96:99]
	ds_read_b128 v[164:167], v243 offset:43008
	v_mfma_f32_16x16x32_bf16 v[84:87], v[140:143], v[172:175], v[84:87]
	v_mfma_f32_16x16x32_bf16 v[76:79], v[148:151], v[172:175], v[76:79]
	v_mfma_f32_16x16x32_bf16 v[72:75], v[156:159], v[172:175], v[72:75]
	s_waitcnt lgkmcnt(3)
	v_mfma_f32_16x16x32_bf16 v[68:71], v[132:135], v[176:179], v[68:71]
	ds_read_b128 v[168:171], v243 offset:45056
	v_mfma_f32_16x16x32_bf16 v[64:67], v[140:143], v[176:179], v[64:67]
	v_mfma_f32_16x16x32_bf16 v[60:63], v[148:151], v[176:179], v[60:63]
	v_mfma_f32_16x16x32_bf16 v[56:59], v[156:159], v[176:179], v[56:59]
	s_waitcnt lgkmcnt(3)
	v_mfma_f32_16x16x32_bf16 v[28:31], v[132:135], v[180:183], v[28:31]
	ds_read_b128 v[172:175], v243 offset:47104
	v_mfma_f32_16x16x32_bf16 v[4:7], v[140:143], v[180:183], v[4:7]
	v_mfma_f32_16x16x32_bf16 v[24:27], v[148:151], v[180:183], v[24:27]
	v_mfma_f32_16x16x32_bf16 v[20:23], v[156:159], v[180:183], v[20:23]
	s_waitcnt lgkmcnt(3)
	v_mfma_f32_16x16x32_bf16 v[0:3], v[132:135], v[160:163], v[0:3]
	v_mfma_f32_16x16x32_bf16 v[8:11], v[140:143], v[160:163], v[8:11]
	v_mfma_f32_16x16x32_bf16 v[16:19], v[148:151], v[160:163], v[16:19]
	v_mfma_f32_16x16x32_bf16 v[36:39], v[156:159], v[160:163], v[36:39]
	s_waitcnt lgkmcnt(2)
	v_mfma_f32_16x16x32_bf16 v[12:15], v[132:135], v[164:167], v[12:15]
	v_mfma_f32_16x16x32_bf16 v[32:35], v[140:143], v[164:167], v[32:35]
	v_mfma_f32_16x16x32_bf16 v[44:47], v[148:151], v[164:167], v[44:47]
	v_mfma_f32_16x16x32_bf16 v[52:55], v[156:159], v[164:167], v[52:55]
	s_waitcnt lgkmcnt(1)
	v_mfma_f32_16x16x32_bf16 v[40:43], v[132:135], v[168:171], v[40:43]
	v_mfma_f32_16x16x32_bf16 v[48:51], v[140:143], v[168:171], v[48:51]
	v_mfma_f32_16x16x32_bf16 v[104:107], v[148:151], v[168:171], v[104:107]
	v_mfma_f32_16x16x32_bf16 v[100:103], v[156:159], v[168:171], v[100:103]
	s_waitcnt lgkmcnt(0)
	v_mfma_f32_16x16x32_bf16 v[92:95], v[132:135], v[172:175], v[92:95]
	v_mfma_f32_16x16x32_bf16 v[88:91], v[140:143], v[172:175], v[88:91]
	v_mfma_f32_16x16x32_bf16 v[80:83], v[148:151], v[172:175], v[80:83]
	v_mfma_f32_16x16x32_bf16 v[124:127], v[156:159], v[172:175], v[124:127]
	s_sub_u32 s1, s1, 1
	s_cmp_lg_u32 s1, 0
	s_cbranch_scc1 .Lg8p3_loop
	s_waitcnt vmcnt(0) lgkmcnt(0)
	s_barrier
	ds_read_b128 v[128:131], v240 offset:0
	ds_read_b128 v[136:139], v240 offset:2048
	ds_read_b128 v[144:147], v240 offset:4096
	ds_read_b128 v[152:155], v240 offset:6144
	ds_read_b128 v[132:135], v241 offset:0
	ds_read_b128 v[140:143], v241 offset:2048
	ds_read_b128 v[148:151], v241 offset:4096
	ds_read_b128 v[156:159], v241 offset:6144
	s_waitcnt lgkmcnt(0)
	s_barrier
	s_add_u32 m0, s0, 65536
	ds_read_b128 v[160:163], v246 offset:0
	global_load_lds_dwordx4 v252, s[100:101]
	s_add_u32 m0, s0, 69632
	ds_read_b128 v[164:167], v246 offset:2048
	global_load_lds_dwordx4 v251, s[100:101]
	s_add_u32 m0, s0, 73728
	ds_read_b128 v[168:171], v246 offset:4096
	global_load_lds_dwordx4 v248, s[100:101]
	s_add_u32 m0, s0, 77824
	ds_read_b128 v[172:175], v246 offset:6144
	global_load_lds_dwordx4 v249, s[100:101]
	s_add_u32 m0, s0, 32768
	s_nop 0
	global_load_lds_dwordx4 v252, s[98:99]
	s_add_u32 m0, s0, 36864
	s_nop 0
	global_load_lds_dwordx4 v251, s[98:99]
	s_add_u32 m0, s0, 40960
	s_nop 0
	global_load_lds_dwordx4 v248, s[98:99]
	s_add_u32 m0, s0, 45056
	s_nop 0
	global_load_lds_dwordx4 v249, s[98:99]
	s_add_u32 m0, s0, 49152
	s_nop 0
	global_load_lds_dwordx4 v250, s[98:99]
	s_add_u32 m0, s0, 53248
	s_nop 0
	global_load_lds_dwordx4 v247, s[98:99]
	s_add_u32 m0, s0, 57344
	s_nop 0
	global_load_lds_dwordx4 v244, s[98:99]
	s_add_u32 m0, s0, 61440
	s_nop 0
	global_load_lds_dwordx4 v245, s[98:99]
	s_add_u32 s98, s98, 0x80
	s_addc_u32 s99, s99, 0
	s_add_u32 s100, s100, 0x80
	s_addc_u32 s101, s101, 0
	s_waitcnt lgkmcnt(3)
	v_mfma_f32_16x16x32_bf16 v[120:123], v[128:131], v[160:163], v[120:123]
	ds_read_b128 v[176:179], v246 offset:8192
	v_mfma_f32_16x16x32_bf16 v[116:119], v[136:139], v[160:163], v[116:119]
	v_mfma_f32_16x16x32_bf16 v[112:115], v[144:147], v[160:163], v[112:115]
	v_mfma_f32_16x16x32_bf16 v[108:111], v[152:155], v[160:163], v[108:111]
	s_waitcnt lgkmcnt(3)
	v_mfma_f32_16x16x32_bf16 v[96:99], v[128:131], v[164:167], v[96:99]
	ds_read_b128 v[180:183], v246 offset:10240
	v_mfma_f32_16x16x32_bf16 v[84:87], v[136:139], v[164:167], v[84:87]
	v_mfma_f32_16x16x32_bf16 v[76:79], v[144:147], v[164:167], v[76:79]
	v_mfma_f32_16x16x32_bf16 v[72:75], v[152:155], v[164:167], v[72:75]
	s_waitcnt lgkmcnt(3)
	v_mfma_f32_16x16x32_bf16 v[68:71], v[128:131], v[168:171], v[68:71]
	ds_read_b128 v[160:163], v246 offset:12288
	v_mfma_f32_16x16x32_bf16 v[64:67], v[136:139], v[168:171], v[64:67]
	v_mfma_f32_16x16x32_bf16 v[60:63], v[144:147], v[168:171], v[60:63]
	v_mfma_f32_16x16x32_bf16 v[56:59], v[152:155], v[168:171], v[56:59]
	s_waitcnt lgkmcnt(3)
	v_mfma_f32_16x16x32_bf16 v[28:31], v[128:131], v[172:175], v[28:31]
	ds_read_b128 v[164:167], v246 offset:14336
	v_mfma_f32_16x16x32_bf16 v[4:7], v[136:139], v[172:175], v[4:7]
	v_mfma_f32_16x16x32_bf16 v[24:27], v[144:147], v[172:175], v[24:27]
	v_mfma_f32_16x16x32_bf16 v[20:23], v[152:155], v[172:175], v[20:23]
	s_waitcnt lgkmcnt(3)
	v_mfma_f32_16x16x32_bf16 v[0:3], v[128:131], v[176:179], v[0:3]
	ds_read_b128 v[168:171], v243 offset:0
	v_mfma_f32_16x16x32_bf16 v[8:11], v[136:139], v[176:179], v[8:11]
	v_mfma_f32_16x16x32_bf16 v[16:19], v[144:147], v[176:179], v[16:19]
	v_mfma_f32_16x16x32_bf16 v[36:39], v[152:155], v[176:179], v[36:39]
	s_waitcnt lgkmcnt(3)
	v_mfma_f32_16x16x32_bf16 v[12:15], v[128:131], v[180:183], v[12:15]
	ds_read_b128 v[172:175], v243 offset:2048
	v_mfma_f32_16x16x32_bf16 v[32:35], v[136:139], v[180:183], v[32:35]
	v_mfma_f32_16x16x32_bf16 v[44:47], v[144:147], v[180:183], v[44:47]
	v_mfma_f32_16x16x32_bf16 v[52:55], v[152:155], v[180:183], v[52:55]
	s_waitcnt lgkmcnt(3)
	v_mfma_f32_16x16x32_bf16 v[40:43], v[128:131], v[160:163], v[40:43]
	ds_read_b128 v[176:179], v243 offset:4096
	v_mfma_f32_16x16x32_bf16 v[48:51], v[136:139], v[160:163], v[48:51]
	v_mfma_f32_16x16x32_bf16 v[104:107], v[144:147], v[160:163], v[104:107]
	v_mfma_f32_16x16x32_bf16 v[100:103], v[152:155], v[160:163], v[100:103]
	s_waitcnt lgkmcnt(3)
	v_mfma_f32_16x16x32_bf16 v[92:95], v[128:131], v[164:167], v[92:95]
	ds_read_b128 v[180:183], v243 offset:6144
	v_mfma_f32_16x16x32_bf16 v[88:91], v[136:139], v[164:167], v[88:91]
	v_mfma_f32_16x16x32_bf16 v[80:83], v[144:147], v[164:167], v[80:83]
	v_mfma_f32_16x16x32_bf16 v[124:127], v[152:155], v[164:167], v[124:127]
	s_waitcnt lgkmcnt(3)
	v_mfma_f32_16x16x32_bf16 v[120:123], v[132:135], v[168:171], v[120:123]
	ds_read_b128 v[160:163], v243 offset:8192
	v_mfma_f32_16x16x32_bf16 v[116:119], v[140:143], v[168:171], v[116:119]
	v_mfma_f32_16x16x32_bf16 v[112:115], v[148:151], v[168:171], v[112:115]
	v_mfma_f32_16x16x32_bf16 v[108:111], v[156:159], v[168:171], v[108:111]
	s_waitcnt lgkmcnt(3)
	v_mfma_f32_16x16x32_bf16 v[96:99], v[132:135], v[172:175], v[96:99]
	ds_read_b128 v[164:167], v243 offset:10240
	v_mfma_f32_16x16x32_bf16 v[84:87], v[140:143], v[172:175], v[84:87]
	v_mfma_f32_16x16x32_bf16 v[76:79], v[148:151], v[172:175], v[76:79]
	v_mfma_f32_16x16x32_bf16 v[72:75], v[156:159], v[172:175], v[72:75]
	s_waitcnt lgkmcnt(3)
	v_mfma_f32_16x16x32_bf16 v[68:71], v[132:135], v[176:179], v[68:71]
	ds_read_b128 v[168:171], v243 offset:12288
	v_mfma_f32_16x16x32_bf16 v[64:67], v[140:143], v[176:179], v[64:67]
	v_mfma_f32_16x16x32_bf16 v[60:63], v[148:151], v[176:179], v[60:63]
	v_mfma_f32_16x16x32_bf16 v[56:59], v[156:159], v[176:179], v[56:59]
	s_waitcnt lgkmcnt(3)
	v_mfma_f32_16x16x32_bf16 v[28:31], v[132:135], v[180:183], v[28:31]
	ds_read_b128 v[172:175], v243 offset:14336
	v_mfma_f32_16x16x32_bf16 v[4:7], v[140:143], v[180:183], v[4:7]
	v_mfma_f32_16x16x32_bf16 v[24:27], v[148:151], v[180:183], v[24:27]
	v_mfma_f32_16x16x32_bf16 v[20:23], v[156:159], v[180:183], v[20:23]
	s_waitcnt lgkmcnt(3)
	v_mfma_f32_16x16x32_bf16 v[0:3], v[132:135], v[160:163], v[0:3]
	v_mfma_f32_16x16x32_bf16 v[8:11], v[140:143], v[160:163], v[8:11]
	v_mfma_f32_16x16x32_bf16 v[16:19], v[148:151], v[160:163], v[16:19]
	v_mfma_f32_16x16x32_bf16 v[36:39], v[156:159], v[160:163], v[36:39]
	s_waitcnt lgkmcnt(2)
	v_mfma_f32_16x16x32_bf16 v[12:15], v[132:135], v[164:167], v[12:15]
	v_mfma_f32_16x16x32_bf16 v[32:35], v[140:143], v[164:167], v[32:35]
	v_mfma_f32_16x16x32_bf16 v[44:47], v[148:151], v[164:167], v[44:47]
	v_mfma_f32_16x16x32_bf16 v[52:55], v[156:159], v[164:167], v[52:55]
	s_waitcnt lgkmcnt(1)
	v_mfma_f32_16x16x32_bf16 v[40:43], v[132:135], v[168:171], v[40:43]
	v_mfma_f32_16x16x32_bf16 v[48:51], v[140:143], v[168:171], v[48:51]
	v_mfma_f32_16x16x32_bf16 v[104:107], v[148:151], v[168:171], v[104:107]
	v_mfma_f32_16x16x32_bf16 v[100:103], v[156:159], v[168:171], v[100:103]
	s_waitcnt lgkmcnt(0)
	v_mfma_f32_16x16x32_bf16 v[92:95], v[132:135], v[172:175], v[92:95]
	v_mfma_f32_16x16x32_bf16 v[88:91], v[140:143], v[172:175], v[88:91]
	v_mfma_f32_16x16x32_bf16 v[80:83], v[148:151], v[172:175], v[80:83]
	v_mfma_f32_16x16x32_bf16 v[124:127], v[156:159], v[172:175], v[124:127]
	s_waitcnt vmcnt(0) lgkmcnt(0)
	s_barrier
	ds_read_b128 v[128:131], v240 offset:0
	ds_read_b128 v[136:139], v240 offset:2048
	ds_read_b128 v[144:147], v240 offset:4096
	ds_read_b128 v[152:155], v240 offset:6144
	ds_read_b128 v[132:135], v241 offset:0
	ds_read_b128 v[140:143], v241 offset:2048
	ds_read_b128 v[148:151], v241 offset:4096
	ds_read_b128 v[156:159], v241 offset:6144
	ds_read_b128 v[160:163], v246 offset:32768
	ds_read_b128 v[164:167], v246 offset:34816
	ds_read_b128 v[168:171], v246 offset:36864
	ds_read_b128 v[172:175], v246 offset:38912
	s_waitcnt lgkmcnt(4)
	s_waitcnt lgkmcnt(3)
	v_mfma_f32_16x16x32_bf16 v[120:123], v[128:131], v[160:163], v[120:123]
	ds_read_b128 v[176:179], v246 offset:40960
	v_mfma_f32_16x16x32_bf16 v[116:119], v[136:139], v[160:163], v[116:119]
	v_mfma_f32_16x16x32_bf16 v[112:115], v[144:147], v[160:163], v[112:115]
	v_mfma_f32_16x16x32_bf16 v[108:111], v[152:155], v[160:163], v[108:111]
	s_waitcnt lgkmcnt(3)
	v_mfma_f32_16x16x32_bf16 v[96:99], v[128:131], v[164:167], v[96:99]
	ds_read_b128 v[180:183], v246 offset:43008
	v_mfma_f32_16x16x32_bf16 v[84:87], v[136:139], v[164:167], v[84:87]
	v_mfma_f32_16x16x32_bf16 v[76:79], v[144:147], v[164:167], v[76:79]
	v_mfma_f32_16x16x32_bf16 v[72:75], v[152:155], v[164:167], v[72:75]
	s_waitcnt lgkmcnt(3)
	v_mfma_f32_16x16x32_bf16 v[68:71], v[128:131], v[168:171], v[68:71]
	ds_read_b128 v[160:163], v246 offset:45056
	v_mfma_f32_16x16x32_bf16 v[64:67], v[136:139], v[168:171], v[64:67]
	v_mfma_f32_16x16x32_bf16 v[60:63], v[144:147], v[168:171], v[60:63]
	v_mfma_f32_16x16x32_bf16 v[56:59], v[152:155], v[168:171], v[56:59]
	s_waitcnt lgkmcnt(3)
	v_mfma_f32_16x16x32_bf16 v[28:31], v[128:131], v[172:175], v[28:31]
	ds_read_b128 v[164:167], v246 offset:47104
	v_mfma_f32_16x16x32_bf16 v[4:7], v[136:139], v[172:175], v[4:7]
	v_mfma_f32_16x16x32_bf16 v[24:27], v[144:147], v[172:175], v[24:27]
	v_mfma_f32_16x16x32_bf16 v[20:23], v[152:155], v[172:175], v[20:23]
	s_waitcnt lgkmcnt(3)
	v_mfma_f32_16x16x32_bf16 v[0:3], v[128:131], v[176:179], v[0:3]
	ds_read_b128 v[168:171], v243 offset:32768
	v_mfma_f32_16x16x32_bf16 v[8:11], v[136:139], v[176:179], v[8:11]
	v_mfma_f32_16x16x32_bf16 v[16:19], v[144:147], v[176:179], v[16:19]
	v_mfma_f32_16x16x32_bf16 v[36:39], v[152:155], v[176:179], v[36:39]
	s_waitcnt lgkmcnt(3)
	v_mfma_f32_16x16x32_bf16 v[12:15], v[128:131], v[180:183], v[12:15]
	ds_read_b128 v[172:175], v243 offset:34816
	v_mfma_f32_16x16x32_bf16 v[32:35], v[136:139], v[180:183], v[32:35]
	v_mfma_f32_16x16x32_bf16 v[44:47], v[144:147], v[180:183], v[44:47]
	v_mfma_f32_16x16x32_bf16 v[52:55], v[152:155], v[180:183], v[52:55]
	s_waitcnt lgkmcnt(3)
	v_mfma_f32_16x16x32_bf16 v[40:43], v[128:131], v[160:163], v[40:43]
	ds_read_b128 v[176:179], v243 offset:36864
	v_mfma_f32_16x16x32_bf16 v[48:51], v[136:139], v[160:163], v[48:51]
	v_mfma_f32_16x16x32_bf16 v[104:107], v[144:147], v[160:163], v[104:107]
	v_mfma_f32_16x16x32_bf16 v[100:103], v[152:155], v[160:163], v[100:103]
	s_waitcnt lgkmcnt(3)
	v_mfma_f32_16x16x32_bf16 v[92:95], v[128:131], v[164:167], v[92:95]
	ds_read_b128 v[180:183], v243 offset:38912
	v_mfma_f32_16x16x32_bf16 v[88:91], v[136:139], v[164:167], v[88:91]
	v_mfma_f32_16x16x32_bf16 v[80:83], v[144:147], v[164:167], v[80:83]
	v_mfma_f32_16x16x32_bf16 v[124:127], v[152:155], v[164:167], v[124:127]
	s_waitcnt lgkmcnt(3)
	v_mfma_f32_16x16x32_bf16 v[120:123], v[132:135], v[168:171], v[120:123]
	ds_read_b128 v[160:163], v243 offset:40960
	v_mfma_f32_16x16x32_bf16 v[116:119], v[140:143], v[168:171], v[116:119]
	v_mfma_f32_16x16x32_bf16 v[112:115], v[148:151], v[168:171], v[112:115]
	v_mfma_f32_16x16x32_bf16 v[108:111], v[156:159], v[168:171], v[108:111]
	s_waitcnt lgkmcnt(3)
	v_mfma_f32_16x16x32_bf16 v[96:99], v[132:135], v[172:175], v[96:99]
	ds_read_b128 v[164:167], v243 offset:43008
	v_mfma_f32_16x16x32_bf16 v[84:87], v[140:143], v[172:175], v[84:87]
	v_mfma_f32_16x16x32_bf16 v[76:79], v[148:151], v[172:175], v[76:79]
	v_mfma_f32_16x16x32_bf16 v[72:75], v[156:159], v[172:175], v[72:75]
	s_waitcnt lgkmcnt(3)
	v_mfma_f32_16x16x32_bf16 v[68:71], v[132:135], v[176:179], v[68:71]
	ds_read_b128 v[168:171], v243 offset:45056
	v_mfma_f32_16x16x32_bf16 v[64:67], v[140:143], v[176:179], v[64:67]
	v_mfma_f32_16x16x32_bf16 v[60:63], v[148:151], v[176:179], v[60:63]
	v_mfma_f32_16x16x32_bf16 v[56:59], v[156:159], v[176:179], v[56:59]
	s_waitcnt lgkmcnt(3)
	v_mfma_f32_16x16x32_bf16 v[28:31], v[132:135], v[180:183], v[28:31]
	ds_read_b128 v[172:175], v243 offset:47104
	v_mfma_f32_16x16x32_bf16 v[4:7], v[140:143], v[180:183], v[4:7]
	v_mfma_f32_16x16x32_bf16 v[24:27], v[148:151], v[180:183], v[24:27]
	v_mfma_f32_16x16x32_bf16 v[20:23], v[156:159], v[180:183], v[20:23]
	s_waitcnt lgkmcnt(3)
	v_mfma_f32_16x16x32_bf16 v[0:3], v[132:135], v[160:163], v[0:3]
	v_mfma_f32_16x16x32_bf16 v[8:11], v[140:143], v[160:163], v[8:11]
	v_mfma_f32_16x16x32_bf16 v[16:19], v[148:151], v[160:163], v[16:19]
	v_mfma_f32_16x16x32_bf16 v[36:39], v[156:159], v[160:163], v[36:39]
	s_waitcnt lgkmcnt(2)
	v_mfma_f32_16x16x32_bf16 v[12:15], v[132:135], v[164:167], v[12:15]
	v_mfma_f32_16x16x32_bf16 v[32:35], v[140:143], v[164:167], v[32:35]
	v_mfma_f32_16x16x32_bf16 v[44:47], v[148:151], v[164:167], v[44:47]
	v_mfma_f32_16x16x32_bf16 v[52:55], v[156:159], v[164:167], v[52:55]
	s_waitcnt lgkmcnt(1)
	v_mfma_f32_16x16x32_bf16 v[40:43], v[132:135], v[168:171], v[40:43]
	v_mfma_f32_16x16x32_bf16 v[48:51], v[140:143], v[168:171], v[48:51]
	v_mfma_f32_16x16x32_bf16 v[104:107], v[148:151], v[168:171], v[104:107]
	v_mfma_f32_16x16x32_bf16 v[100:103], v[156:159], v[168:171], v[100:103]
	s_waitcnt lgkmcnt(0)
	v_mfma_f32_16x16x32_bf16 v[92:95], v[132:135], v[172:175], v[92:95]
	v_mfma_f32_16x16x32_bf16 v[88:91], v[140:143], v[172:175], v[88:91]
	v_mfma_f32_16x16x32_bf16 v[80:83], v[148:151], v[172:175], v[80:83]
	v_mfma_f32_16x16x32_bf16 v[124:127], v[156:159], v[172:175], v[124:127]
	s_nop 7
	s_nop 7
	s_barrier
	ds_write_b64 v194, v[192:193]
	s_movk_i32 s0, 0xc00
	v_mov_b32_e32 v172, v84
	v_mov_b32_e32 v173, v85
	v_mov_b32_e32 v174, v86
	v_mov_b32_e32 v175, v87
	v_mov_b32_e32 v176, v76
	v_mov_b32_e32 v177, v77
	v_mov_b32_e32 v178, v78
	v_mov_b32_e32 v179, v79
	v_mov_b32_e32 v180, v72
	v_mov_b32_e32 v181, v73
	v_mov_b32_e32 v182, v74
	v_mov_b32_e32 v183, v75
	v_mov_b32_e32 v168, v56
	v_mov_b32_e32 v169, v57
	v_mov_b32_e32 v170, v58
	v_mov_b32_e32 v171, v59
	v_mov_b32_e32 v76, v64
	v_mov_b32_e32 v77, v65
	v_mov_b32_e32 v78, v66
	v_mov_b32_e32 v79, v67
	v_mov_b32_e32 v64, v4
	v_mov_b32_e32 v65, v5
	v_mov_b32_e32 v66, v6
	v_mov_b32_e32 v67, v7
	v_mov_b32_e32 v72, v68
	v_mov_b32_e32 v73, v69
	v_mov_b32_e32 v74, v70
	v_mov_b32_e32 v75, v71
	v_mov_b32_e32 v84, v60
	v_mov_b32_e32 v85, v61
	v_mov_b32_e32 v86, v62
	v_mov_b32_e32 v87, v63
	v_mov_b32_e32 v60, v28
	v_mov_b32_e32 v61, v29
	v_mov_b32_e32 v62, v30
	v_mov_b32_e32 v63, v31
	v_mov_b32_e32 v68, v24
	v_mov_b32_e32 v69, v25
	v_mov_b32_e32 v70, v26
	v_mov_b32_e32 v71, v27
	v_mov_b32_e32 v164, v20
	v_mov_b32_e32 v165, v21
	v_mov_b32_e32 v166, v22
	v_mov_b32_e32 v167, v23
	v_mov_b32_e32 v56, v0
	v_mov_b32_e32 v57, v1
	v_mov_b32_e32 v58, v2
	v_mov_b32_e32 v59, v3
	v_mov_b32_e32 v20, v12
	v_mov_b32_e32 v21, v13
	v_mov_b32_e32 v22, v14
	v_mov_b32_e32 v23, v15
	v_mov_b32_e32 v24, v32
	v_mov_b32_e32 v25, v33
	v_mov_b32_e32 v26, v34
	v_mov_b32_e32 v27, v35
	v_mov_b32_e32 v28, v44
	v_mov_b32_e32 v29, v45
	v_mov_b32_e32 v30, v46
	v_mov_b32_e32 v31, v47
	v_mov_b32_e32 v32, v52
	v_mov_b32_e32 v33, v53
	v_mov_b32_e32 v34, v54
	v_mov_b32_e32 v35, v55
	v_mov_b32_e32 v156, v8
	v_mov_b32_e32 v157, v9
	v_mov_b32_e32 v158, v10
	v_mov_b32_e32 v159, v11
	v_mov_b32_e32 v8, v40
	v_mov_b32_e32 v9, v41
	v_mov_b32_e32 v10, v42
	v_mov_b32_e32 v11, v43
	v_mov_b32_e32 v160, v16
	v_mov_b32_e32 v161, v17
	v_mov_b32_e32 v162, v18
	v_mov_b32_e32 v163, v19
	v_mov_b32_e32 v12, v48
	v_mov_b32_e32 v13, v49
	v_mov_b32_e32 v14, v50
	v_mov_b32_e32 v15, v51
	v_mov_b32_e32 v16, v104
	v_mov_b32_e32 v17, v105
	v_mov_b32_e32 v18, v106
	v_mov_b32_e32 v19, v107
	v_mov_b32_e32 v136, v100
	v_mov_b32_e32 v137, v101
	v_mov_b32_e32 v138, v102
	v_mov_b32_e32 v139, v103
	v_mov_b32_e32 v0, v92
	v_mov_b32_e32 v1, v93
	v_mov_b32_e32 v2, v94
	v_mov_b32_e32 v3, v95
	v_mov_b32_e32 v4, v88
	v_mov_b32_e32 v5, v89
	v_mov_b32_e32 v6, v90
	v_mov_b32_e32 v7, v91
	v_mov_b32_e32 v128, v80
	v_mov_b32_e32 v129, v81
	v_mov_b32_e32 v130, v82
	v_mov_b32_e32 v131, v83
	v_mov_b32_e32 v132, v120
	v_mov_b32_e32 v133, v121
	v_mov_b32_e32 v134, v122
	v_mov_b32_e32 v135, v123
	v_mov_b32_e32 v120, v116
	v_mov_b32_e32 v121, v117
	v_mov_b32_e32 v122, v118
	v_mov_b32_e32 v123, v119
	v_mov_b32_e32 v116, v112
	v_mov_b32_e32 v117, v113
	v_mov_b32_e32 v118, v114
	v_mov_b32_e32 v119, v115
	v_mov_b32_e32 v112, v108
	v_mov_b32_e32 v113, v109
	v_mov_b32_e32 v114, v110
	v_mov_b32_e32 v115, v111
	v_mov_b32_e32 v108, v96
	v_mov_b32_e32 v109, v97
	v_mov_b32_e32 v110, v98
	v_mov_b32_e32 v111, v99
	v_mov_b32_e32 v104, v172
	v_mov_b32_e32 v105, v173
	v_mov_b32_e32 v106, v174
	v_mov_b32_e32 v107, v175
	v_mov_b32_e32 v100, v176
	v_mov_b32_e32 v101, v177
	v_mov_b32_e32 v102, v178
	v_mov_b32_e32 v103, v179
	v_mov_b32_e32 v96, v180
	v_mov_b32_e32 v97, v181
	v_mov_b32_e32 v98, v182
	v_mov_b32_e32 v99, v183
	v_mov_b32_e32 v92, v72
	v_mov_b32_e32 v93, v73
	v_mov_b32_e32 v94, v74
	v_mov_b32_e32 v95, v75
	v_mov_b32_e32 v88, v76
	v_mov_b32_e32 v89, v77
	v_mov_b32_e32 v90, v78
	v_mov_b32_e32 v91, v79
	v_mov_b32_e32 v80, v168
	v_mov_b32_e32 v81, v169
	v_mov_b32_e32 v82, v170
	v_mov_b32_e32 v83, v171
	v_mov_b32_e32 v76, v60
	v_mov_b32_e32 v77, v61
	v_mov_b32_e32 v78, v62
	v_mov_b32_e32 v79, v63
	v_mov_b32_e32 v72, v64
	v_mov_b32_e32 v73, v65
	v_mov_b32_e32 v74, v66
	v_mov_b32_e32 v75, v67
	v_mov_b32_e32 v64, v164
	v_mov_b32_e32 v65, v165
	v_mov_b32_e32 v66, v166
	v_mov_b32_e32 v67, v167
	v_mov_b32_e32 v60, v56
	v_mov_b32_e32 v61, v57
	v_mov_b32_e32 v62, v58
	v_mov_b32_e32 v63, v59
	v_mov_b32_e32 v56, v156
	v_mov_b32_e32 v57, v157
	v_mov_b32_e32 v58, v158
	v_mov_b32_e32 v59, v159
	v_mov_b32_e32 v52, v160
	v_mov_b32_e32 v53, v161
	v_mov_b32_e32 v54, v162
	v_mov_b32_e32 v55, v163
	v_mov_b32_e32 v48, v36
	v_mov_b32_e32 v49, v37
	v_mov_b32_e32 v50, v38
	v_mov_b32_e32 v51, v39
	v_mov_b32_e32 v44, v20
	v_mov_b32_e32 v45, v21
	v_mov_b32_e32 v46, v22
	v_mov_b32_e32 v47, v23
	v_mov_b32_e32 v40, v24
	v_mov_b32_e32 v41, v25
	v_mov_b32_e32 v42, v26
	v_mov_b32_e32 v43, v27
	v_mov_b32_e32 v36, v28
	v_mov_b32_e32 v37, v29
	v_mov_b32_e32 v38, v30
	v_mov_b32_e32 v39, v31
	v_mov_b32_e32 v28, v8
	v_mov_b32_e32 v29, v9
	v_mov_b32_e32 v30, v10
	v_mov_b32_e32 v31, v11
	v_mov_b32_e32 v8, v136
	v_mov_b32_e32 v9, v137
	v_mov_b32_e32 v10, v138
	v_mov_b32_e32 v11, v139
	v_mov_b32_e32 v24, v12
	v_mov_b32_e32 v25, v13
	v_mov_b32_e32 v26, v14
	v_mov_b32_e32 v27, v15
	v_mov_b32_e32 v20, v16
	v_mov_b32_e32 v21, v17
	v_mov_b32_e32 v22, v18
	v_mov_b32_e32 v23, v19
	v_mov_b32_e32 v16, v0
	v_mov_b32_e32 v17, v1
	v_mov_b32_e32 v18, v2
	v_mov_b32_e32 v19, v3
	v_mov_b32_e32 v12, v4
	v_mov_b32_e32 v13, v5
	v_mov_b32_e32 v14, v6
	v_mov_b32_e32 v15, v7
	v_mov_b32_e32 v4, v128
	v_mov_b32_e32 v5, v129
	v_mov_b32_e32 v6, v130
	v_mov_b32_e32 v7, v131
	v_mov_b32_e32 v0, v124
	v_mov_b32_e32 v1, v125
	v_mov_b32_e32 v2, v126
	v_mov_b32_e32 v3, v127
	s_nop 2
	v_or_b32_e32 v124, s10, v202
	v_cmp_ne_u32_e64 s[0:1], s0, v124
	s_and_saveexec_b64 s[6:7], s[0:1]
	s_xor_b64 s[6:7], exec, s[6:7]
	s_or_saveexec_b64 s[6:7], s[6:7]
	v_add_u32_e32 v126, s4, v201
	v_or_b32_e32 v124, v126, v197
	v_lshlrev_b32_e32 v124, 6, v124
	v_ashrrev_i32_e32 v125, 31, v124
	v_or_b32_e32 v184, s10, v203
	v_lshl_add_u64 v[124:125], v[124:125], 2, s[30:31]
	s_xor_b64 exec, exec, s[6:7]
	s_cbranch_execz .LBB0_418
	v_lshl_add_u64 v[128:129], v[184:185], 2, v[124:125]
	v_add_co_u32_e32 v128, vcc, 0xffffd000, v128
	s_nop 1
	v_addc_co_u32_e32 v129, vcc, -1, v129, vcc
	global_store_dwordx4 v[128:129], v[132:135], off

.Lg8p11_loop:
	s_waitcnt vmcnt(0) lgkmcnt(0)
	s_barrier
	ds_read_b128 v[128:131], v248 offset:0
	ds_read_b128 v[148:151], v248 offset:2048
	ds_read_b128 v[156:159], v248 offset:4096
	ds_read_b128 v[164:167], v248 offset:6144
	ds_read_b128 v[144:147], v249 offset:0
	ds_read_b128 v[152:155], v249 offset:2048
	ds_read_b128 v[160:163], v249 offset:4096
	ds_read_b128 v[168:171], v249 offset:6144
	s_waitcnt lgkmcnt(0)
	s_barrier
	s_add_u32 m0, s2, 65536
	ds_read_b128 v[172:175], v252 offset:0
	global_load_lds_dwordx4 v134, s[100:101]
	s_add_u32 m0, s2, 69632
	ds_read_b128 v[176:179], v252 offset:2048
	global_load_lds_dwordx4 v142, s[100:101]
	s_add_u32 m0, s2, 73728
	ds_read_b128 v[188:191], v252 offset:4096
	global_load_lds_dwordx4 v143, s[100:101]
	s_add_u32 m0, s2, 77824
	ds_read_b128 v[220:223], v252 offset:6144
	global_load_lds_dwordx4 v180, s[100:101]
	s_add_u32 m0, s2, 32768
	s_nop 0
	global_load_lds_dwordx4 v134, s[98:99]
	s_add_u32 m0, s2, 36864
	s_nop 0
	global_load_lds_dwordx4 v142, s[98:99]
	s_add_u32 m0, s2, 40960
	s_nop 0
	global_load_lds_dwordx4 v143, s[98:99]
	s_add_u32 m0, s2, 45056
	s_nop 0
	global_load_lds_dwordx4 v180, s[98:99]
	s_add_u32 m0, s2, 49152
	s_nop 0
	global_load_lds_dwordx4 v215, s[98:99]
	s_add_u32 m0, s2, 53248
	s_nop 0
	global_load_lds_dwordx4 v216, s[98:99]
	s_add_u32 m0, s2, 57344
	s_nop 0
	global_load_lds_dwordx4 v217, s[98:99]
	s_add_u32 m0, s2, 61440
	s_nop 0
	global_load_lds_dwordx4 v218, s[98:99]
	s_add_u32 s98, s98, 0x80
	s_addc_u32 s99, s99, 0
	s_add_u32 s100, s100, 0x80
	s_addc_u32 s101, s101, 0
	s_waitcnt lgkmcnt(3)
	v_mfma_f32_16x16x32_bf16 v[124:127], v[128:131], v[172:175], v[124:127]
	ds_read_b128 v[224:227], v252 offset:8192
	v_mfma_f32_16x16x32_bf16 v[120:123], v[148:151], v[172:175], v[120:123]
	v_mfma_f32_16x16x32_bf16 v[116:119], v[156:159], v[172:175], v[116:119]
	v_mfma_f32_16x16x32_bf16 v[112:115], v[164:167], v[172:175], v[112:115]
	s_waitcnt lgkmcnt(3)
	v_mfma_f32_16x16x32_bf16 v[108:111], v[128:131], v[176:179], v[108:111]
	ds_read_b128 v[228:231], v252 offset:10240
	v_mfma_f32_16x16x32_bf16 v[104:107], v[148:151], v[176:179], v[104:107]
	v_mfma_f32_16x16x32_bf16 v[100:103], v[156:159], v[176:179], v[100:103]
	v_mfma_f32_16x16x32_bf16 v[96:99], v[164:167], v[176:179], v[96:99]
	s_waitcnt lgkmcnt(3)
	v_mfma_f32_16x16x32_bf16 v[92:95], v[128:131], v[188:191], v[92:95]
	ds_read_b128 v[172:175], v252 offset:12288
	v_mfma_f32_16x16x32_bf16 v[88:91], v[148:151], v[188:191], v[88:91]
	v_mfma_f32_16x16x32_bf16 v[84:87], v[156:159], v[188:191], v[84:87]
	v_mfma_f32_16x16x32_bf16 v[80:83], v[164:167], v[188:191], v[80:83]
	s_waitcnt lgkmcnt(3)
	v_mfma_f32_16x16x32_bf16 v[72:75], v[128:131], v[220:223], v[72:75]
	ds_read_b128 v[176:179], v252 offset:14336
	v_mfma_f32_16x16x32_bf16 v[68:71], v[148:151], v[220:223], v[68:71]
	v_mfma_f32_16x16x32_bf16 v[64:67], v[156:159], v[220:223], v[64:67]
	v_mfma_f32_16x16x32_bf16 v[60:63], v[164:167], v[220:223], v[60:63]
	s_waitcnt lgkmcnt(3)
	v_mfma_f32_16x16x32_bf16 v[56:59], v[128:131], v[224:227], v[56:59]
	ds_read_b128 v[188:191], v251 offset:0
	v_mfma_f32_16x16x32_bf16 v[52:55], v[148:151], v[224:227], v[52:55]
	v_mfma_f32_16x16x32_bf16 v[48:51], v[156:159], v[224:227], v[48:51]
	v_mfma_f32_16x16x32_bf16 v[44:47], v[164:167], v[224:227], v[44:47]
	s_waitcnt lgkmcnt(3)
	v_mfma_f32_16x16x32_bf16 v[40:43], v[128:131], v[228:231], v[40:43]
	ds_read_b128 v[220:223], v251 offset:2048
	v_mfma_f32_16x16x32_bf16 v[36:39], v[148:151], v[228:231], v[36:39]
	v_mfma_f32_16x16x32_bf16 v[32:35], v[156:159], v[228:231], v[32:35]
	v_mfma_f32_16x16x32_bf16 v[28:31], v[164:167], v[228:231], v[28:31]
	s_waitcnt lgkmcnt(3)
	v_mfma_f32_16x16x32_bf16 v[24:27], v[128:131], v[172:175], v[24:27]
	ds_read_b128 v[224:227], v251 offset:4096
	v_mfma_f32_16x16x32_bf16 v[20:23], v[148:151], v[172:175], v[20:23]
	v_mfma_f32_16x16x32_bf16 v[16:19], v[156:159], v[172:175], v[16:19]
	v_mfma_f32_16x16x32_bf16 v[12:15], v[164:167], v[172:175], v[12:15]
	s_waitcnt lgkmcnt(3)
	v_mfma_f32_16x16x32_bf16 v[8:11], v[128:131], v[176:179], v[8:11]
	ds_read_b128 v[228:231], v251 offset:6144
	v_mfma_f32_16x16x32_bf16 v[4:7], v[148:151], v[176:179], v[4:7]
	v_mfma_f32_16x16x32_bf16 v[0:3], v[156:159], v[176:179], v[0:3]
	v_mfma_f32_16x16x32_bf16 v[76:79], v[164:167], v[176:179], v[76:79]
	s_waitcnt lgkmcnt(3)
	v_mfma_f32_16x16x32_bf16 v[124:127], v[144:147], v[188:191], v[124:127]
	ds_read_b128 v[172:175], v251 offset:8192
	v_mfma_f32_16x16x32_bf16 v[120:123], v[152:155], v[188:191], v[120:123]
	v_mfma_f32_16x16x32_bf16 v[116:119], v[160:163], v[188:191], v[116:119]
	v_mfma_f32_16x16x32_bf16 v[112:115], v[168:171], v[188:191], v[112:115]
	s_waitcnt lgkmcnt(3)
	v_mfma_f32_16x16x32_bf16 v[108:111], v[144:147], v[220:223], v[108:111]
	ds_read_b128 v[176:179], v251 offset:10240
	v_mfma_f32_16x16x32_bf16 v[104:107], v[152:155], v[220:223], v[104:107]
	v_mfma_f32_16x16x32_bf16 v[100:103], v[160:163], v[220:223], v[100:103]
	v_mfma_f32_16x16x32_bf16 v[96:99], v[168:171], v[220:223], v[96:99]
	s_waitcnt lgkmcnt(3)
	v_mfma_f32_16x16x32_bf16 v[92:95], v[144:147], v[224:227], v[92:95]
	ds_read_b128 v[188:191], v251 offset:12288
	v_mfma_f32_16x16x32_bf16 v[88:91], v[152:155], v[224:227], v[88:91]
	v_mfma_f32_16x16x32_bf16 v[84:87], v[160:163], v[224:227], v[84:87]
	v_mfma_f32_16x16x32_bf16 v[80:83], v[168:171], v[224:227], v[80:83]
	s_waitcnt lgkmcnt(3)
	v_mfma_f32_16x16x32_bf16 v[72:75], v[144:147], v[228:231], v[72:75]
	ds_read_b128 v[220:223], v251 offset:14336
	v_mfma_f32_16x16x32_bf16 v[68:71], v[152:155], v[228:231], v[68:71]
	v_mfma_f32_16x16x32_bf16 v[64:67], v[160:163], v[228:231], v[64:67]
	v_mfma_f32_16x16x32_bf16 v[60:63], v[168:171], v[228:231], v[60:63]
	s_waitcnt lgkmcnt(3)
	v_mfma_f32_16x16x32_bf16 v[56:59], v[144:147], v[172:175], v[56:59]
	v_mfma_f32_16x16x32_bf16 v[52:55], v[152:155], v[172:175], v[52:55]
	v_mfma_f32_16x16x32_bf16 v[48:51], v[160:163], v[172:175], v[48:51]
	v_mfma_f32_16x16x32_bf16 v[44:47], v[168:171], v[172:175], v[44:47]
	s_waitcnt lgkmcnt(2)
	v_mfma_f32_16x16x32_bf16 v[40:43], v[144:147], v[176:179], v[40:43]
	v_mfma_f32_16x16x32_bf16 v[36:39], v[152:155], v[176:179], v[36:39]
	v_mfma_f32_16x16x32_bf16 v[32:35], v[160:163], v[176:179], v[32:35]
	v_mfma_f32_16x16x32_bf16 v[28:31], v[168:171], v[176:179], v[28:31]
	s_waitcnt lgkmcnt(1)
	v_mfma_f32_16x16x32_bf16 v[24:27], v[144:147], v[188:191], v[24:27]
	v_mfma_f32_16x16x32_bf16 v[20:23], v[152:155], v[188:191], v[20:23]
	v_mfma_f32_16x16x32_bf16 v[16:19], v[160:163], v[188:191], v[16:19]
	v_mfma_f32_16x16x32_bf16 v[12:15], v[168:171], v[188:191], v[12:15]
	s_waitcnt lgkmcnt(0)
	v_mfma_f32_16x16x32_bf16 v[8:11], v[144:147], v[220:223], v[8:11]
	v_mfma_f32_16x16x32_bf16 v[4:7], v[152:155], v[220:223], v[4:7]
	v_mfma_f32_16x16x32_bf16 v[0:3], v[160:163], v[220:223], v[0:3]
	v_mfma_f32_16x16x32_bf16 v[76:79], v[168:171], v[220:223], v[76:79]
	s_waitcnt vmcnt(0) lgkmcnt(0)
	s_barrier
	ds_read_b128 v[128:131], v248 offset:0
	ds_read_b128 v[148:151], v248 offset:2048
	ds_read_b128 v[156:159], v248 offset:4096
	ds_read_b128 v[164:167], v248 offset:6144
	ds_read_b128 v[144:147], v249 offset:0
	ds_read_b128 v[152:155], v249 offset:2048
	ds_read_b128 v[160:163], v249 offset:4096
	ds_read_b128 v[168:171], v249 offset:6144
	s_waitcnt lgkmcnt(0)
	s_barrier
	s_add_u32 m0, s2, 65536
	ds_read_b128 v[172:175], v252 offset:32768
	global_load_lds_dwordx4 v134, s[100:101]
	s_add_u32 m0, s2, 69632
	ds_read_b128 v[176:179], v252 offset:34816
	global_load_lds_dwordx4 v142, s[100:101]
	s_add_u32 m0, s2, 73728
	ds_read_b128 v[188:191], v252 offset:36864
	global_load_lds_dwordx4 v143, s[100:101]
	s_add_u32 m0, s2, 77824
	ds_read_b128 v[220:223], v252 offset:38912
	global_load_lds_dwordx4 v180, s[100:101]
	s_add_u32 m0, s2, 0
	s_nop 0
	global_load_lds_dwordx4 v134, s[98:99]
	s_add_u32 m0, s2, 4096
	s_nop 0
	global_load_lds_dwordx4 v142, s[98:99]
	s_add_u32 m0, s2, 8192
	s_nop 0
	global_load_lds_dwordx4 v143, s[98:99]
	s_add_u32 m0, s2, 12288
	s_nop 0
	global_load_lds_dwordx4 v180, s[98:99]
	s_add_u32 m0, s2, 16384
	s_nop 0
	global_load_lds_dwordx4 v215, s[98:99]
	s_add_u32 m0, s2, 20480
	s_nop 0
	global_load_lds_dwordx4 v216, s[98:99]
	s_add_u32 m0, s2, 24576
	s_nop 0
	global_load_lds_dwordx4 v217, s[98:99]
	s_add_u32 m0, s2, 28672
	s_nop 0
	global_load_lds_dwordx4 v218, s[98:99]
	s_add_u32 s98, s98, 0x80
	s_addc_u32 s99, s99, 0
	s_add_u32 s100, s100, 0x80
	s_addc_u32 s101, s101, 0
	s_waitcnt lgkmcnt(3)
	v_mfma_f32_16x16x32_bf16 v[124:127], v[128:131], v[172:175], v[124:127]
	ds_read_b128 v[224:227], v252 offset:40960
	v_mfma_f32_16x16x32_bf16 v[120:123], v[148:151], v[172:175], v[120:123]
	v_mfma_f32_16x16x32_bf16 v[116:119], v[156:159], v[172:175], v[116:119]
	v_mfma_f32_16x16x32_bf16 v[112:115], v[164:167], v[172:175], v[112:115]
	s_waitcnt lgkmcnt(3)
	v_mfma_f32_16x16x32_bf16 v[108:111], v[128:131], v[176:179], v[108:111]
	ds_read_b128 v[228:231], v252 offset:43008
	v_mfma_f32_16x16x32_bf16 v[104:107], v[148:151], v[176:179], v[104:107]
	v_mfma_f32_16x16x32_bf16 v[100:103], v[156:159], v[176:179], v[100:103]
	v_mfma_f32_16x16x32_bf16 v[96:99], v[164:167], v[176:179], v[96:99]
	s_waitcnt lgkmcnt(3)
	v_mfma_f32_16x16x32_bf16 v[92:95], v[128:131], v[188:191], v[92:95]
	ds_read_b128 v[172:175], v252 offset:45056
	v_mfma_f32_16x16x32_bf16 v[88:91], v[148:151], v[188:191], v[88:91]
	v_mfma_f32_16x16x32_bf16 v[84:87], v[156:159], v[188:191], v[84:87]
	v_mfma_f32_16x16x32_bf16 v[80:83], v[164:167], v[188:191], v[80:83]
	s_waitcnt lgkmcnt(3)
	v_mfma_f32_16x16x32_bf16 v[72:75], v[128:131], v[220:223], v[72:75]
	ds_read_b128 v[176:179], v252 offset:47104
	v_mfma_f32_16x16x32_bf16 v[68:71], v[148:151], v[220:223], v[68:71]
	v_mfma_f32_16x16x32_bf16 v[64:67], v[156:159], v[220:223], v[64:67]
	v_mfma_f32_16x16x32_bf16 v[60:63], v[164:167], v[220:223], v[60:63]
	s_waitcnt lgkmcnt(3)
	v_mfma_f32_16x16x32_bf16 v[56:59], v[128:131], v[224:227], v[56:59]
	ds_read_b128 v[188:191], v251 offset:32768
	v_mfma_f32_16x16x32_bf16 v[52:55], v[148:151], v[224:227], v[52:55]
	v_mfma_f32_16x16x32_bf16 v[48:51], v[156:159], v[224:227], v[48:51]
	v_mfma_f32_16x16x32_bf16 v[44:47], v[164:167], v[224:227], v[44:47]
	s_waitcnt lgkmcnt(3)
	v_mfma_f32_16x16x32_bf16 v[40:43], v[128:131], v[228:231], v[40:43]
	ds_read_b128 v[220:223], v251 offset:34816
	v_mfma_f32_16x16x32_bf16 v[36:39], v[148:151], v[228:231], v[36:39]
	v_mfma_f32_16x16x32_bf16 v[32:35], v[156:159], v[228:231], v[32:35]
	v_mfma_f32_16x16x32_bf16 v[28:31], v[164:167], v[228:231], v[28:31]
	s_waitcnt lgkmcnt(3)
	v_mfma_f32_16x16x32_bf16 v[24:27], v[128:131], v[172:175], v[24:27]
	ds_read_b128 v[224:227], v251 offset:36864
	v_mfma_f32_16x16x32_bf16 v[20:23], v[148:151], v[172:175], v[20:23]
	v_mfma_f32_16x16x32_bf16 v[16:19], v[156:159], v[172:175], v[16:19]
	v_mfma_f32_16x16x32_bf16 v[12:15], v[164:167], v[172:175], v[12:15]
	s_waitcnt lgkmcnt(3)
	v_mfma_f32_16x16x32_bf16 v[8:11], v[128:131], v[176:179], v[8:11]
	ds_read_b128 v[228:231], v251 offset:38912
	v_mfma_f32_16x16x32_bf16 v[4:7], v[148:151], v[176:179], v[4:7]
	v_mfma_f32_16x16x32_bf16 v[0:3], v[156:159], v[176:179], v[0:3]
	v_mfma_f32_16x16x32_bf16 v[76:79], v[164:167], v[176:179], v[76:79]
	s_waitcnt lgkmcnt(3)
	v_mfma_f32_16x16x32_bf16 v[124:127], v[144:147], v[188:191], v[124:127]
	ds_read_b128 v[172:175], v251 offset:40960
	v_mfma_f32_16x16x32_bf16 v[120:123], v[152:155], v[188:191], v[120:123]
	v_mfma_f32_16x16x32_bf16 v[116:119], v[160:163], v[188:191], v[116:119]
	v_mfma_f32_16x16x32_bf16 v[112:115], v[168:171], v[188:191], v[112:115]
	s_waitcnt lgkmcnt(3)
	v_mfma_f32_16x16x32_bf16 v[108:111], v[144:147], v[220:223], v[108:111]
	ds_read_b128 v[176:179], v251 offset:43008
	v_mfma_f32_16x16x32_bf16 v[104:107], v[152:155], v[220:223], v[104:107]
	v_mfma_f32_16x16x32_bf16 v[100:103], v[160:163], v[220:223], v[100:103]
	v_mfma_f32_16x16x32_bf16 v[96:99], v[168:171], v[220:223], v[96:99]
	s_waitcnt lgkmcnt(3)
	v_mfma_f32_16x16x32_bf16 v[92:95], v[144:147], v[224:227], v[92:95]
	ds_read_b128 v[188:191], v251 offset:45056
	v_mfma_f32_16x16x32_bf16 v[88:91], v[152:155], v[224:227], v[88:91]
	v_mfma_f32_16x16x32_bf16 v[84:87], v[160:163], v[224:227], v[84:87]
	v_mfma_f32_16x16x32_bf16 v[80:83], v[168:171], v[224:227], v[80:83]
	s_waitcnt lgkmcnt(3)
	v_mfma_f32_16x16x32_bf16 v[72:75], v[144:147], v[228:231], v[72:75]
	ds_read_b128 v[220:223], v251 offset:47104
	v_mfma_f32_16x16x32_bf16 v[68:71], v[152:155], v[228:231], v[68:71]
	v_mfma_f32_16x16x32_bf16 v[64:67], v[160:163], v[228:231], v[64:67]
	v_mfma_f32_16x16x32_bf16 v[60:63], v[168:171], v[228:231], v[60:63]
	s_waitcnt lgkmcnt(3)
	v_mfma_f32_16x16x32_bf16 v[56:59], v[144:147], v[172:175], v[56:59]
	v_mfma_f32_16x16x32_bf16 v[52:55], v[152:155], v[172:175], v[52:55]
	v_mfma_f32_16x16x32_bf16 v[48:51], v[160:163], v[172:175], v[48:51]
	v_mfma_f32_16x16x32_bf16 v[44:47], v[168:171], v[172:175], v[44:47]
	s_waitcnt lgkmcnt(2)
	v_mfma_f32_16x16x32_bf16 v[40:43], v[144:147], v[176:179], v[40:43]
	v_mfma_f32_16x16x32_bf16 v[36:39], v[152:155], v[176:179], v[36:39]
	v_mfma_f32_16x16x32_bf16 v[32:35], v[160:163], v[176:179], v[32:35]
	v_mfma_f32_16x16x32_bf16 v[28:31], v[168:171], v[176:179], v[28:31]
	s_waitcnt lgkmcnt(1)
	v_mfma_f32_16x16x32_bf16 v[24:27], v[144:147], v[188:191], v[24:27]
	v_mfma_f32_16x16x32_bf16 v[20:23], v[152:155], v[188:191], v[20:23]
	v_mfma_f32_16x16x32_bf16 v[16:19], v[160:163], v[188:191], v[16:19]
	v_mfma_f32_16x16x32_bf16 v[12:15], v[168:171], v[188:191], v[12:15]
	s_waitcnt lgkmcnt(0)
	v_mfma_f32_16x16x32_bf16 v[8:11], v[144:147], v[220:223], v[8:11]
	v_mfma_f32_16x16x32_bf16 v[4:7], v[152:155], v[220:223], v[4:7]
	v_mfma_f32_16x16x32_bf16 v[0:3], v[160:163], v[220:223], v[0:3]
	v_mfma_f32_16x16x32_bf16 v[76:79], v[168:171], v[220:223], v[76:79]
	s_sub_u32 s3, s3, 1
	s_cmp_lg_u32 s3, 0
	s_cbranch_scc1 .Lg8p11_loop
	s_waitcnt vmcnt(0) lgkmcnt(0)
	s_barrier
	ds_read_b128 v[128:131], v248 offset:0
	ds_read_b128 v[148:151], v248 offset:2048
	ds_read_b128 v[156:159], v248 offset:4096
	ds_read_b128 v[164:167], v248 offset:6144
	ds_read_b128 v[144:147], v249 offset:0
	ds_read_b128 v[152:155], v249 offset:2048
	ds_read_b128 v[160:163], v249 offset:4096
	ds_read_b128 v[168:171], v249 offset:6144
	s_waitcnt lgkmcnt(0)
	s_barrier
	s_add_u32 m0, s2, 65536
	ds_read_b128 v[172:175], v252 offset:0
	global_load_lds_dwordx4 v134, s[100:101]
	s_add_u32 m0, s2, 69632
	ds_read_b128 v[176:179], v252 offset:2048
	global_load_lds_dwordx4 v142, s[100:101]
	s_add_u32 m0, s2, 73728
	ds_read_b128 v[188:191], v252 offset:4096
	global_load_lds_dwordx4 v143, s[100:101]
	s_add_u32 m0, s2, 77824
	ds_read_b128 v[220:223], v252 offset:6144
	global_load_lds_dwordx4 v180, s[100:101]
	s_add_u32 m0, s2, 32768
	s_nop 0
	global_load_lds_dwordx4 v134, s[98:99]
	s_add_u32 m0, s2, 36864
	s_nop 0
	global_load_lds_dwordx4 v142, s[98:99]
	s_add_u32 m0, s2, 40960
	s_nop 0
	global_load_lds_dwordx4 v143, s[98:99]
	s_add_u32 m0, s2, 45056
	s_nop 0
	global_load_lds_dwordx4 v180, s[98:99]
	s_add_u32 m0, s2, 49152
	s_nop 0
	global_load_lds_dwordx4 v215, s[98:99]
	s_add_u32 m0, s2, 53248
	s_nop 0
	global_load_lds_dwordx4 v216, s[98:99]
	s_add_u32 m0, s2, 57344
	s_nop 0
	global_load_lds_dwordx4 v217, s[98:99]
	s_add_u32 m0, s2, 61440
	s_nop 0
	global_load_lds_dwordx4 v218, s[98:99]
	s_add_u32 s98, s98, 0x80
	s_addc_u32 s99, s99, 0
	s_add_u32 s100, s100, 0x80
	s_addc_u32 s101, s101, 0
	s_waitcnt lgkmcnt(3)
	v_mfma_f32_16x16x32_bf16 v[124:127], v[128:131], v[172:175], v[124:127]
	ds_read_b128 v[224:227], v252 offset:8192
	v_mfma_f32_16x16x32_bf16 v[120:123], v[148:151], v[172:175], v[120:123]
	v_mfma_f32_16x16x32_bf16 v[116:119], v[156:159], v[172:175], v[116:119]
	v_mfma_f32_16x16x32_bf16 v[112:115], v[164:167], v[172:175], v[112:115]
	s_waitcnt lgkmcnt(3)
	v_mfma_f32_16x16x32_bf16 v[108:111], v[128:131], v[176:179], v[108:111]
	ds_read_b128 v[228:231], v252 offset:10240
	v_mfma_f32_16x16x32_bf16 v[104:107], v[148:151], v[176:179], v[104:107]
	v_mfma_f32_16x16x32_bf16 v[100:103], v[156:159], v[176:179], v[100:103]
	v_mfma_f32_16x16x32_bf16 v[96:99], v[164:167], v[176:179], v[96:99]
	s_waitcnt lgkmcnt(3)
	v_mfma_f32_16x16x32_bf16 v[92:95], v[128:131], v[188:191], v[92:95]
	ds_read_b128 v[172:175], v252 offset:12288
	v_mfma_f32_16x16x32_bf16 v[88:91], v[148:151], v[188:191], v[88:91]
	v_mfma_f32_16x16x32_bf16 v[84:87], v[156:159], v[188:191], v[84:87]
	v_mfma_f32_16x16x32_bf16 v[80:83], v[164:167], v[188:191], v[80:83]
	s_waitcnt lgkmcnt(3)
	v_mfma_f32_16x16x32_bf16 v[72:75], v[128:131], v[220:223], v[72:75]
	ds_read_b128 v[176:179], v252 offset:14336
	v_mfma_f32_16x16x32_bf16 v[68:71], v[148:151], v[220:223], v[68:71]
	v_mfma_f32_16x16x32_bf16 v[64:67], v[156:159], v[220:223], v[64:67]
	v_mfma_f32_16x16x32_bf16 v[60:63], v[164:167], v[220:223], v[60:63]
	s_waitcnt lgkmcnt(3)
	v_mfma_f32_16x16x32_bf16 v[56:59], v[128:131], v[224:227], v[56:59]
	ds_read_b128 v[188:191], v251 offset:0
	v_mfma_f32_16x16x32_bf16 v[52:55], v[148:151], v[224:227], v[52:55]
	v_mfma_f32_16x16x32_bf16 v[48:51], v[156:159], v[224:227], v[48:51]
	v_mfma_f32_16x16x32_bf16 v[44:47], v[164:167], v[224:227], v[44:47]
	s_waitcnt lgkmcnt(3)
	v_mfma_f32_16x16x32_bf16 v[40:43], v[128:131], v[228:231], v[40:43]
	ds_read_b128 v[220:223], v251 offset:2048
	v_mfma_f32_16x16x32_bf16 v[36:39], v[148:151], v[228:231], v[36:39]
	v_mfma_f32_16x16x32_bf16 v[32:35], v[156:159], v[228:231], v[32:35]
	v_mfma_f32_16x16x32_bf16 v[28:31], v[164:167], v[228:231], v[28:31]
	s_waitcnt lgkmcnt(3)
	v_mfma_f32_16x16x32_bf16 v[24:27], v[128:131], v[172:175], v[24:27]
	ds_read_b128 v[224:227], v251 offset:4096
	v_mfma_f32_16x16x32_bf16 v[20:23], v[148:151], v[172:175], v[20:23]
	v_mfma_f32_16x16x32_bf16 v[16:19], v[156:159], v[172:175], v[16:19]
	v_mfma_f32_16x16x32_bf16 v[12:15], v[164:167], v[172:175], v[12:15]
	s_waitcnt lgkmcnt(3)
	v_mfma_f32_16x16x32_bf16 v[8:11], v[128:131], v[176:179], v[8:11]
	ds_read_b128 v[228:231], v251 offset:6144
	v_mfma_f32_16x16x32_bf16 v[4:7], v[148:151], v[176:179], v[4:7]
	v_mfma_f32_16x16x32_bf16 v[0:3], v[156:159], v[176:179], v[0:3]
	v_mfma_f32_16x16x32_bf16 v[76:79], v[164:167], v[176:179], v[76:79]
	s_waitcnt lgkmcnt(3)
	v_mfma_f32_16x16x32_bf16 v[124:127], v[144:147], v[188:191], v[124:127]
	ds_read_b128 v[172:175], v251 offset:8192
	v_mfma_f32_16x16x32_bf16 v[120:123], v[152:155], v[188:191], v[120:123]
	v_mfma_f32_16x16x32_bf16 v[116:119], v[160:163], v[188:191], v[116:119]
	v_mfma_f32_16x16x32_bf16 v[112:115], v[168:171], v[188:191], v[112:115]
	s_waitcnt lgkmcnt(3)
	v_mfma_f32_16x16x32_bf16 v[108:111], v[144:147], v[220:223], v[108:111]
	ds_read_b128 v[176:179], v251 offset:10240
	v_mfma_f32_16x16x32_bf16 v[104:107], v[152:155], v[220:223], v[104:107]
	v_mfma_f32_16x16x32_bf16 v[100:103], v[160:163], v[220:223], v[100:103]
	v_mfma_f32_16x16x32_bf16 v[96:99], v[168:171], v[220:223], v[96:99]
	s_waitcnt lgkmcnt(3)
	v_mfma_f32_16x16x32_bf16 v[92:95], v[144:147], v[224:227], v[92:95]
	ds_read_b128 v[188:191], v251 offset:12288
	v_mfma_f32_16x16x32_bf16 v[88:91], v[152:155], v[224:227], v[88:91]
	v_mfma_f32_16x16x32_bf16 v[84:87], v[160:163], v[224:227], v[84:87]
	v_mfma_f32_16x16x32_bf16 v[80:83], v[168:171], v[224:227], v[80:83]
	s_waitcnt lgkmcnt(3)
	v_mfma_f32_16x16x32_bf16 v[72:75], v[144:147], v[228:231], v[72:75]
	ds_read_b128 v[220:223], v251 offset:14336
	v_mfma_f32_16x16x32_bf16 v[68:71], v[152:155], v[228:231], v[68:71]
	v_mfma_f32_16x16x32_bf16 v[64:67], v[160:163], v[228:231], v[64:67]
	v_mfma_f32_16x16x32_bf16 v[60:63], v[168:171], v[228:231], v[60:63]
	s_waitcnt lgkmcnt(3)
	v_mfma_f32_16x16x32_bf16 v[56:59], v[144:147], v[172:175], v[56:59]
	v_mfma_f32_16x16x32_bf16 v[52:55], v[152:155], v[172:175], v[52:55]
	v_mfma_f32_16x16x32_bf16 v[48:51], v[160:163], v[172:175], v[48:51]
	v_mfma_f32_16x16x32_bf16 v[44:47], v[168:171], v[172:175], v[44:47]
	s_waitcnt lgkmcnt(2)
	v_mfma_f32_16x16x32_bf16 v[40:43], v[144:147], v[176:179], v[40:43]
	v_mfma_f32_16x16x32_bf16 v[36:39], v[152:155], v[176:179], v[36:39]
	v_mfma_f32_16x16x32_bf16 v[32:35], v[160:163], v[176:179], v[32:35]
	v_mfma_f32_16x16x32_bf16 v[28:31], v[168:171], v[176:179], v[28:31]
	s_waitcnt lgkmcnt(1)
	v_mfma_f32_16x16x32_bf16 v[24:27], v[144:147], v[188:191], v[24:27]
	v_mfma_f32_16x16x32_bf16 v[20:23], v[152:155], v[188:191], v[20:23]
	v_mfma_f32_16x16x32_bf16 v[16:19], v[160:163], v[188:191], v[16:19]
	v_mfma_f32_16x16x32_bf16 v[12:15], v[168:171], v[188:191], v[12:15]
	s_waitcnt lgkmcnt(0)
	v_mfma_f32_16x16x32_bf16 v[8:11], v[144:147], v[220:223], v[8:11]
	v_mfma_f32_16x16x32_bf16 v[4:7], v[152:155], v[220:223], v[4:7]
	v_mfma_f32_16x16x32_bf16 v[0:3], v[160:163], v[220:223], v[0:3]
	v_mfma_f32_16x16x32_bf16 v[76:79], v[168:171], v[220:223], v[76:79]
	s_waitcnt vmcnt(0) lgkmcnt(0)
	s_barrier
	ds_read_b128 v[128:131], v248 offset:0
	ds_read_b128 v[148:151], v248 offset:2048
	ds_read_b128 v[156:159], v248 offset:4096
	ds_read_b128 v[164:167], v248 offset:6144
	ds_read_b128 v[144:147], v249 offset:0
	ds_read_b128 v[152:155], v249 offset:2048
	ds_read_b128 v[160:163], v249 offset:4096
	ds_read_b128 v[168:171], v249 offset:6144
	ds_read_b128 v[172:175], v252 offset:32768
	ds_read_b128 v[176:179], v252 offset:34816
	ds_read_b128 v[188:191], v252 offset:36864
	ds_read_b128 v[220:223], v252 offset:38912
	s_waitcnt lgkmcnt(4)
	s_waitcnt lgkmcnt(3)
	v_mfma_f32_16x16x32_bf16 v[124:127], v[128:131], v[172:175], v[124:127]
	ds_read_b128 v[224:227], v252 offset:40960
	v_mfma_f32_16x16x32_bf16 v[120:123], v[148:151], v[172:175], v[120:123]
	v_mfma_f32_16x16x32_bf16 v[116:119], v[156:159], v[172:175], v[116:119]
	v_mfma_f32_16x16x32_bf16 v[112:115], v[164:167], v[172:175], v[112:115]
	s_waitcnt lgkmcnt(3)
	v_mfma_f32_16x16x32_bf16 v[108:111], v[128:131], v[176:179], v[108:111]
	ds_read_b128 v[228:231], v252 offset:43008
	v_mfma_f32_16x16x32_bf16 v[104:107], v[148:151], v[176:179], v[104:107]
	v_mfma_f32_16x16x32_bf16 v[100:103], v[156:159], v[176:179], v[100:103]
	v_mfma_f32_16x16x32_bf16 v[96:99], v[164:167], v[176:179], v[96:99]
	s_waitcnt lgkmcnt(3)
	v_mfma_f32_16x16x32_bf16 v[92:95], v[128:131], v[188:191], v[92:95]
	ds_read_b128 v[172:175], v252 offset:45056
	v_mfma_f32_16x16x32_bf16 v[88:91], v[148:151], v[188:191], v[88:91]
	v_mfma_f32_16x16x32_bf16 v[84:87], v[156:159], v[188:191], v[84:87]
	v_mfma_f32_16x16x32_bf16 v[80:83], v[164:167], v[188:191], v[80:83]
	s_waitcnt lgkmcnt(3)
	v_mfma_f32_16x16x32_bf16 v[72:75], v[128:131], v[220:223], v[72:75]
	ds_read_b128 v[176:179], v252 offset:47104
	v_mfma_f32_16x16x32_bf16 v[68:71], v[148:151], v[220:223], v[68:71]
	v_mfma_f32_16x16x32_bf16 v[64:67], v[156:159], v[220:223], v[64:67]
	v_mfma_f32_16x16x32_bf16 v[60:63], v[164:167], v[220:223], v[60:63]
	s_waitcnt lgkmcnt(3)
	v_mfma_f32_16x16x32_bf16 v[56:59], v[128:131], v[224:227], v[56:59]
	ds_read_b128 v[188:191], v251 offset:32768
	v_mfma_f32_16x16x32_bf16 v[52:55], v[148:151], v[224:227], v[52:55]
	v_mfma_f32_16x16x32_bf16 v[48:51], v[156:159], v[224:227], v[48:51]
	v_mfma_f32_16x16x32_bf16 v[44:47], v[164:167], v[224:227], v[44:47]
	s_waitcnt lgkmcnt(3)
	v_mfma_f32_16x16x32_bf16 v[40:43], v[128:131], v[228:231], v[40:43]
	ds_read_b128 v[220:223], v251 offset:34816
	v_mfma_f32_16x16x32_bf16 v[36:39], v[148:151], v[228:231], v[36:39]
	v_mfma_f32_16x16x32_bf16 v[32:35], v[156:159], v[228:231], v[32:35]
	v_mfma_f32_16x16x32_bf16 v[28:31], v[164:167], v[228:231], v[28:31]
	s_waitcnt lgkmcnt(3)
	v_mfma_f32_16x16x32_bf16 v[24:27], v[128:131], v[172:175], v[24:27]
	ds_read_b128 v[224:227], v251 offset:36864
	v_mfma_f32_16x16x32_bf16 v[20:23], v[148:151], v[172:175], v[20:23]
	v_mfma_f32_16x16x32_bf16 v[16:19], v[156:159], v[172:175], v[16:19]
	v_mfma_f32_16x16x32_bf16 v[12:15], v[164:167], v[172:175], v[12:15]
	s_waitcnt lgkmcnt(3)
	v_mfma_f32_16x16x32_bf16 v[8:11], v[128:131], v[176:179], v[8:11]
	ds_read_b128 v[228:231], v251 offset:38912
	v_mfma_f32_16x16x32_bf16 v[4:7], v[148:151], v[176:179], v[4:7]
	v_mfma_f32_16x16x32_bf16 v[0:3], v[156:159], v[176:179], v[0:3]
	v_mfma_f32_16x16x32_bf16 v[76:79], v[164:167], v[176:179], v[76:79]
	s_waitcnt lgkmcnt(3)
	v_mfma_f32_16x16x32_bf16 v[124:127], v[144:147], v[188:191], v[124:127]
	ds_read_b128 v[172:175], v251 offset:40960
	v_mfma_f32_16x16x32_bf16 v[120:123], v[152:155], v[188:191], v[120:123]
	v_mfma_f32_16x16x32_bf16 v[116:119], v[160:163], v[188:191], v[116:119]
	v_mfma_f32_16x16x32_bf16 v[112:115], v[168:171], v[188:191], v[112:115]
	s_waitcnt lgkmcnt(3)
	v_mfma_f32_16x16x32_bf16 v[108:111], v[144:147], v[220:223], v[108:111]
	ds_read_b128 v[176:179], v251 offset:43008
	v_mfma_f32_16x16x32_bf16 v[104:107], v[152:155], v[220:223], v[104:107]
	v_mfma_f32_16x16x32_bf16 v[100:103], v[160:163], v[220:223], v[100:103]
	v_mfma_f32_16x16x32_bf16 v[96:99], v[168:171], v[220:223], v[96:99]
	s_waitcnt lgkmcnt(3)
	v_mfma_f32_16x16x32_bf16 v[92:95], v[144:147], v[224:227], v[92:95]
	ds_read_b128 v[188:191], v251 offset:45056
	v_mfma_f32_16x16x32_bf16 v[88:91], v[152:155], v[224:227], v[88:91]
	v_mfma_f32_16x16x32_bf16 v[84:87], v[160:163], v[224:227], v[84:87]
	v_mfma_f32_16x16x32_bf16 v[80:83], v[168:171], v[224:227], v[80:83]
	s_waitcnt lgkmcnt(3)
	v_mfma_f32_16x16x32_bf16 v[72:75], v[144:147], v[228:231], v[72:75]
	ds_read_b128 v[220:223], v251 offset:47104
	v_mfma_f32_16x16x32_bf16 v[68:71], v[152:155], v[228:231], v[68:71]
	v_mfma_f32_16x16x32_bf16 v[64:67], v[160:163], v[228:231], v[64:67]
	v_mfma_f32_16x16x32_bf16 v[60:63], v[168:171], v[228:231], v[60:63]
	s_waitcnt lgkmcnt(3)
	v_mfma_f32_16x16x32_bf16 v[56:59], v[144:147], v[172:175], v[56:59]
	v_mfma_f32_16x16x32_bf16 v[52:55], v[152:155], v[172:175], v[52:55]
	v_mfma_f32_16x16x32_bf16 v[48:51], v[160:163], v[172:175], v[48:51]
	v_mfma_f32_16x16x32_bf16 v[44:47], v[168:171], v[172:175], v[44:47]
	s_waitcnt lgkmcnt(2)
	v_mfma_f32_16x16x32_bf16 v[40:43], v[144:147], v[176:179], v[40:43]
	v_mfma_f32_16x16x32_bf16 v[36:39], v[152:155], v[176:179], v[36:39]
	v_mfma_f32_16x16x32_bf16 v[32:35], v[160:163], v[176:179], v[32:35]
	v_mfma_f32_16x16x32_bf16 v[28:31], v[168:171], v[176:179], v[28:31]
	s_waitcnt lgkmcnt(1)
	v_mfma_f32_16x16x32_bf16 v[24:27], v[144:147], v[188:191], v[24:27]
	v_mfma_f32_16x16x32_bf16 v[20:23], v[152:155], v[188:191], v[20:23]
	v_mfma_f32_16x16x32_bf16 v[16:19], v[160:163], v[188:191], v[16:19]
	v_mfma_f32_16x16x32_bf16 v[12:15], v[168:171], v[188:191], v[12:15]
	s_waitcnt lgkmcnt(0)
	v_mfma_f32_16x16x32_bf16 v[8:11], v[144:147], v[220:223], v[8:11]
	v_mfma_f32_16x16x32_bf16 v[4:7], v[152:155], v[220:223], v[4:7]
	v_mfma_f32_16x16x32_bf16 v[0:3], v[160:163], v[220:223], v[0:3]
	v_mfma_f32_16x16x32_bf16 v[76:79], v[168:171], v[220:223], v[76:79]
	s_nop 7
	s_nop 7
	s_barrier
	ds_write_b64 v234, v[232:233]
	v_or_b32_e32 v180, s22, v194
	v_cmp_lt_i32_e64 s[4:5], s52, v180
	v_mov_b32_e32 v144, v76
	v_mov_b32_e32 v145, v77
	v_mov_b32_e32 v146, v78
	v_mov_b32_e32 v147, v79
	v_add_u32_e32 v134, s0, v192
	v_or_b32_e32 v128, v134, v193
	v_ashrrev_i32_e32 v129, 31, v128
	v_cmp_gt_i32_e64 s[12:13], s51, v128
	v_lshlrev_b64 v[130:131], 10, v[128:129]
	v_mov_b32_e32 v76, v72
	v_mov_b32_e32 v77, v73
	v_mov_b32_e32 v78, v74
	v_mov_b32_e32 v79, v75
	v_mov_b32_e32 v72, v68
	v_mov_b32_e32 v73, v69
	v_mov_b32_e32 v74, v70
	v_mov_b32_e32 v75, v71
	v_mov_b32_e32 v68, v64
	v_mov_b32_e32 v69, v65
	v_mov_b32_e32 v70, v66
	v_mov_b32_e32 v71, v67
	v_mov_b32_e32 v64, v60
	v_mov_b32_e32 v65, v61
	v_mov_b32_e32 v66, v62
	v_mov_b32_e32 v67, v63
	v_mov_b32_e32 v60, v56
	v_mov_b32_e32 v61, v57
	v_mov_b32_e32 v62, v58
	v_mov_b32_e32 v63, v59
	v_mov_b32_e32 v56, v52
	v_mov_b32_e32 v57, v53
	v_mov_b32_e32 v58, v54
	v_mov_b32_e32 v59, v55
	v_mov_b32_e32 v52, v48
	v_mov_b32_e32 v53, v49
	v_mov_b32_e32 v54, v50
	v_mov_b32_e32 v55, v51
	v_mov_b32_e32 v48, v44
	v_mov_b32_e32 v49, v45
	v_mov_b32_e32 v50, v46
	v_mov_b32_e32 v51, v47
	v_mov_b32_e32 v44, v40
	v_mov_b32_e32 v45, v41
	v_mov_b32_e32 v46, v42
	v_mov_b32_e32 v47, v43
	v_mov_b32_e32 v40, v36
	v_mov_b32_e32 v41, v37
	v_mov_b32_e32 v42, v38
	v_mov_b32_e32 v43, v39
	v_mov_b32_e32 v36, v32
	v_mov_b32_e32 v37, v33
	v_mov_b32_e32 v38, v34
	v_mov_b32_e32 v39, v35
	v_mov_b32_e32 v32, v28
	v_mov_b32_e32 v33, v29
	v_mov_b32_e32 v34, v30
	v_mov_b32_e32 v35, v31
	v_mov_b32_e32 v28, v24
	v_mov_b32_e32 v29, v25
	v_mov_b32_e32 v30, v26
	v_mov_b32_e32 v31, v27
	v_mov_b32_e32 v24, v20
	v_mov_b32_e32 v25, v21
	v_mov_b32_e32 v26, v22
	v_mov_b32_e32 v27, v23
	v_mov_b32_e32 v20, v16
	v_mov_b32_e32 v21, v17
	v_mov_b32_e32 v22, v18
	v_mov_b32_e32 v23, v19
	v_mov_b32_e32 v16, v12
	v_mov_b32_e32 v17, v13
	v_mov_b32_e32 v18, v14
	v_mov_b32_e32 v19, v15
	v_mov_b32_e32 v12, v8
	v_mov_b32_e32 v13, v9
	v_mov_b32_e32 v14, v10
	v_mov_b32_e32 v15, v11
	v_mov_b32_e32 v8, v4
	v_mov_b32_e32 v9, v5
	v_mov_b32_e32 v10, v6
	v_mov_b32_e32 v11, v7
	v_mov_b32_e32 v4, v0
	v_mov_b32_e32 v5, v1
	v_mov_b32_e32 v6, v2
	v_mov_b32_e32 v7, v3
	v_mov_b32_e32 v0, v144
	v_mov_b32_e32 v1, v145
	v_mov_b32_e32 v2, v146
	v_mov_b32_e32 v3, v147
	s_and_saveexec_b64 s[0:1], s[4:5]
	s_cbranch_execz .LBB0_1254
	s_cmpk_gt_u32 s22, 0xcff
	s_mov_b64 s[2:3], -1
	s_cbranch_scc0 .LBB0_1251
	v_add_u32_e32 v132, 0xfffff300, v180
	v_mov_b64_e32 v[136:137], s[16:17]
	v_mad_u64_u32 v[138:139], s[2:3], v132, s53, v[136:137]
	v_lshlrev_b64 v[140:141], 1, v[128:129]
	v_cvt_pk_bf16_f32 v133, v124, s0
	v_lshl_add_u64 v[138:139], v[138:139], 0, v[140:141]
	v_add_u32_e32 v135, 0xfffff301, v180
	global_store_short v[138:139], v133, off
	v_mad_u64_u32 v[138:139], s[2:3], v135, s53, v[136:137]
	v_cvt_pk_bf16_f32 v133, v125, s0
	v_lshl_add_u64 v[138:139], v[138:139], 0, v[140:141]
	v_add_u32_e32 v135, 0xfffff302, v180
	global_store_short v[138:139], v133, off
	v_mad_u64_u32 v[138:139], s[2:3], v135, s53, v[136:137]
	v_add_u32_e32 v135, 0xfffff303, v180
	v_cvt_pk_bf16_f32 v133, v126, s0
	v_lshl_add_u64 v[138:139], v[138:139], 0, v[140:141]
	v_mad_u64_u32 v[136:137], s[2:3], v135, s53, v[136:137]
	global_store_short v[138:139], v133, off
	v_cvt_pk_bf16_f32 v133, v127, s0
	v_lshl_add_u64 v[136:137], v[136:137], 0, v[140:141]
	global_store_short v[136:137], v133, off
	s_and_saveexec_b64 s[2:3], s[12:13]
	s_cbranch_execz .LBB0_1250
	v_mov_b32_e32 v133, v181
	v_lshl_add_u64 v[136:137], s[20:21], 0, v[130:131]
	v_lshl_add_u64 v[132:133], v[132:133], 2, v[136:137]
	global_store_dwordx4 v[132:133], v[124:127], off
